# phase 0 and phase 1 overlapped: pass A of the phase-0 item loop computes only the adaLN modulation, then half the workgroups run rmsnorm first and the remaining weight preprocessing second, the other
# speedup vs baseline: 1.0207x; 1.0207x over previous
.LBB0_5:
	s_or_b64 exec, exec, s[4:5]
	s_mov_b32 s101, 0
	s_mov_b32 s100, 0x60
	s_mov_b32 s99, s81
.Lp0_enter:
	s_load_dwordx16 s[52:67], s[0:1], 0x0
	s_load_dwordx16 s[4:19], s[0:1], 0x40
	s_load_dwordx16 s[36:51], s[0:1], 0x80
	s_cmp_ge_i32 s99, s100
	s_waitcnt lgkmcnt(0)
	v_writelane_b32 v241, s4, 18
	s_nop 1
	v_writelane_b32 v241, s5, 19
	v_writelane_b32 v241, s6, 20
	v_writelane_b32 v241, s7, 21
	v_writelane_b32 v241, s8, 22
	v_writelane_b32 v241, s9, 23
	v_writelane_b32 v241, s10, 24
	v_writelane_b32 v241, s11, 25
	v_writelane_b32 v241, s12, 26
	v_writelane_b32 v241, s13, 27
	v_writelane_b32 v241, s14, 28
	v_writelane_b32 v241, s15, 29
	v_writelane_b32 v241, s16, 30
	v_writelane_b32 v241, s17, 31
	v_writelane_b32 v241, s18, 32
	v_writelane_b32 v241, s19, 33
	v_writelane_b32 v241, s36, 34
	s_nop 1
	v_writelane_b32 v241, s37, 35
	v_writelane_b32 v241, s38, 36
	v_writelane_b32 v241, s39, 37
	v_writelane_b32 v241, s40, 38
	v_writelane_b32 v241, s41, 39
	v_writelane_b32 v241, s42, 40
	v_writelane_b32 v241, s43, 41
	v_writelane_b32 v241, s44, 42
	v_writelane_b32 v241, s45, 43
	v_writelane_b32 v241, s46, 44
	v_writelane_b32 v241, s47, 45
	v_writelane_b32 v241, s48, 46
	v_writelane_b32 v241, s49, 47
	v_writelane_b32 v241, s50, 48
	v_writelane_b32 v241, s51, 49
	v_writelane_b32 v241, s81, 50
	v_writelane_b32 v241, s82, 51
	s_nop 1
	v_writelane_b32 v241, s83, 52
	v_writelane_b32 v241, s96, 53
	s_nop 1
	v_writelane_b32 v241, s97, 54
	v_writelane_b32 v241, s52, 55
	s_nop 1
	v_writelane_b32 v241, s53, 56
	v_writelane_b32 v241, s54, 57
	v_writelane_b32 v240, s61, 0
	v_writelane_b32 v241, s55, 58
	v_writelane_b32 v240, s62, 1
	v_writelane_b32 v241, s56, 59
	v_writelane_b32 v240, s63, 2
	v_writelane_b32 v241, s57, 60
	v_writelane_b32 v240, s64, 3
	v_writelane_b32 v241, s58, 61
	v_writelane_b32 v240, s65, 4
	v_writelane_b32 v241, s59, 62
	v_writelane_b32 v240, s66, 5
	v_writelane_b32 v241, s60, 63
	v_writelane_b32 v240, s67, 6
	s_cbranch_scc1 .LBB0_92
	s_load_dwordx16 s[4:19], s[0:1], 0xc0
	v_writelane_b32 v240, s78, 7
	s_waitcnt lgkmcnt(0)
	s_mov_b32 s7, 0x3fe45f30
	v_lshrrev_b32_e32 v1, 8, v193
	v_writelane_b32 v240, s79, 8
	s_add_u32 s2, s14, 0x1000
	s_addc_u32 s3, s15, 0
	v_writelane_b32 v240, s2, 9
	s_mov_b32 s8, 0
	v_mov_b32_e32 v35, 0
	v_writelane_b32 v240, s3, 10
	s_add_u32 s2, s14, 0x2000
	s_addc_u32 s3, s15, 0
	v_writelane_b32 v240, s2, 11
	v_lshl_add_u32 v82, v1, 16, 0
	s_mov_b32 s96, 0x6dc9c883
	v_writelane_b32 v240, s3, 12
	s_add_u32 s2, s14, 0x3000
	s_addc_u32 s3, s15, 0
	v_writelane_b32 v240, s2, 13
	s_mov_b32 s4, 0x54442d18
	s_lshl_b32 s33, s82, 5
	v_writelane_b32 v240, s3, 14
	v_writelane_b32 v240, s6, 15
	s_lshl_b32 s2, s99, 1
	v_add_u32_e32 v2, s2, v1
	v_writelane_b32 v240, s7, 16
	s_mov_b32 s7, 0xbff921fb
	v_writelane_b32 v240, s6, 17
	v_add_u32_e32 v83, 0xfffff540, v2
	v_lshlrev_b32_e32 v2, 4, v1
	v_writelane_b32 v240, s7, 18
	v_writelane_b32 v240, s8, 19
	s_lshl_b32 s3, s82, 1
	v_lshlrev_b32_e32 v84, 4, v83
	v_writelane_b32 v240, s9, 20
	v_add_u32_e32 v85, 0x8100, v82
	v_add_u16_e32 v86, s2, v1
	v_add_u32_e32 v87, 0x4100, v82
	v_lshl_add_u32 v88, s99, 5, v2
	v_mov_b32_e32 v106, v35
	v_mov_b32_e32 v107, v35
	v_mov_b32_e32 v108, v35
	v_mov_b32_e32 v109, v35
	s_mov_b32 s34, 0x3fb8aa3b
	s_mov_b32 s35, 0xc2ce8ed0
	s_mov_b32 s68, 0x42b17218
	s_mov_b32 s97, 0x3fc45f30
	s_mov_b32 s5, 0xc01921fb
	s_brev_b32 s69, 18
	s_mov_b32 s70, 0xfe5163ab
	s_mov_b32 s71, 0x3c439041
	s_mov_b32 s72, 0xdb629599
	s_mov_b32 s73, 0xf534ddc0
	s_mov_b32 s74, 0xfc2757d1
	s_mov_b32 s75, 0x4e441529
	s_mov_b32 s76, 0xa2f9836e
	s_mov_b32 s77, 0x3fc90fda
	s_mov_b32 s78, 0x3f22f983
	s_mov_b32 s79, 0xbfc90fda
	v_mov_b32_e32 v89, 0x3c0881c4
	v_mov_b32_e32 v90, 0xbab64f3b
	s_brev_b32 s80, 1
	s_mov_b32 s2, s99
	s_movk_i32 s81, 0x1f8
	s_movk_i32 s83, 0x7fff
	v_mov_b32_e32 v91, 0x7f800000
	v_not_b32_e32 v92, 63
	v_not_b32_e32 v93, 31
	v_mov_b32_e32 v94, 0x7fc00000
	v_mov_b32_e32 v95, 1
	v_mov_b32_e32 v96, 0x40100000
	v_mov_b32_e32 v97, 0x3ff00000
	v_mov_b32_e32 v36, 0xfca7ab0c
	v_mov_b32_e32 v37, 0x3e928af3
	v_mov_b32_e32 v38, 0x623fde64
	v_mov_b32_e32 v39, 0x3ec71dee
	v_mov_b32_e32 v40, 0x7c89e6b0
	v_mov_b32_e32 v41, 0x3efa0199
	v_mov_b32_e32 v42, 0x14761f6e
	v_mov_b32_e32 v43, 0x3f2a01a0
	v_mov_b32_e32 v44, 0x1852b7b0
	v_mov_b32_e32 v45, 0x3f56c16c
	v_mov_b32_e32 v46, 0x11122322
	v_mov_b32_e32 v47, 0x3f811111
	v_mov_b32_e32 v48, 0x555502a1
	v_mov_b32_e32 v49, 0x3fa55555
	v_mov_b32_e32 v50, 0x55555511
	v_mov_b32_e32 v51, 0x3fc55555
	v_mov_b32_e32 v52, 11
	v_mov_b32_e32 v53, 0x3fe00000
	v_mov_b32_e32 v98, 0x7ff00000
	v_mov_b32_e32 v54, 0x9037ab78
	v_mov_b32_e32 v55, 0x3e21eeb6
	v_mov_b32_e32 v56, 0xa17f65f6
	v_mov_b32_e32 v57, 0xbe927e4f
	v_mov_b32_e32 v58, 0x19f4ec90
	v_mov_b32_e32 v59, 0x3efa01a0
	v_mov_b32_e32 v60, 0x16c16967
	v_mov_b32_e32 v61, 0xbf56c16c
	v_mov_b32_e32 v62, 0x55555555
	v_mov_b32_e32 v64, 0xb42fdfa7
	v_mov_b32_e32 v65, 0xbe5ae600
	v_mov_b32_e32 v66, 0x796cde01
	v_mov_b32_e32 v67, 0x3ec71de3
	v_mov_b32_e32 v68, 0x19e83e5c
	v_mov_b32_e32 v69, 0xbf2a01a0
	v_mov_b32_e32 v70, 0x11110bb3
	v_mov_b32_e32 v99, 0x7ff80000
	v_mov_b32_e32 v100, 0x2000
	s_movk_i32 s82, 0x208
	s_mov_b32 s65, 0x3ff921fb
	s_mov_b32 s67, 0x3c91a626
	s_mov_b32 s64, 0x33145c07
	v_writelane_b32 v240, s10, 21
	v_writelane_b32 v240, s11, 22
	s_branch .LBB0_9

.LBB0_8:
	s_or_b64 exec, exec, s[6:7]
	s_load_dwordx2 s[6:7], s[0:1], 0x160
	v_add_u32_e32 v83, s3, v83
	v_add_u32_e32 v84, s33, v84
	v_add_u16_e32 v86, s3, v86
	v_add_u32_e32 v88, s33, v88
	s_waitcnt lgkmcnt(0)
	s_add_i32 s2, s2, s6
	s_cmp_lt_i32 s2, s100
	s_cbranch_scc0 .LBB0_91

.LBB0_92:
	s_load_dwordx2 s[6:7], s[0:1], 0x158
	s_load_dwordx8 s[36:43], s[0:1], 0x138
	s_cmp_eq_u32 s101, 0
	s_cbranch_scc1 .Lst_cont0
	s_waitcnt lgkmcnt(0)
	s_cmp_eq_u32 s101, 2
	s_cbranch_scc1 .Lst_b_to_p1
	s_cmpk_lg_i32 s82, 0x100
	s_cselect_b64 s[0:1], -1, 0
	v_writelane_b32 v240, s0, 11
	v_writelane_b32 v240, s1, 12
	s_cmp_lt_i32 s81, 32
	s_cselect_b64 s[0:1], -1, 0
	s_branch .LBB0_179
.Lst_b_to_p1:
	s_mov_b32 s101, 3
	s_branch .Lp1_enter
.Lst_cont0:
	v_readlane_b32 s8, v241, 0
	v_readlane_b32 s20, v241, 12
	v_readlane_b32 s21, v241, 13
	s_cmp_lg_u64 s[20:21], 0
	v_readlane_b32 s9, v241, 1
	v_readlane_b32 s10, v241, 2
	v_readlane_b32 s11, v241, 3
	v_readlane_b32 s12, v241, 4
	v_readlane_b32 s13, v241, 5
	v_readlane_b32 s14, v241, 6
	v_readlane_b32 s15, v241, 7
	v_readlane_b32 s16, v241, 8
	v_readlane_b32 s17, v241, 9
	v_readlane_b32 s18, v241, 10
	v_readlane_b32 s19, v241, 11
	v_readlane_b32 s22, v241, 14
	v_readlane_b32 s23, v241, 15
	s_cbranch_scc1 .LBB0_104
	v_lshrrev_b32_e32 v1, 20, v0
	v_lshrrev_b32_e32 v0, 10, v0
	v_or_b32_e32 v0, v0, v1
	s_movk_i32 s0, 0x3ff
	v_and_or_b32 v0, v0, s0, v193
	v_cmp_eq_u32_e32 vcc, 0, v0
	s_waitcnt lgkmcnt(0)
	s_barrier
	s_and_saveexec_b64 s[0:1], vcc
	s_cbranch_execz .LBB0_103
	buffer_wbl2 sc1
	s_waitcnt vmcnt(0)
	s_load_dwordx2 s[4:5], s[78:79], 0x58
	v_mov_b32_e32 v2, 0
	s_mov_b64 s[8:9], exec
	v_mbcnt_lo_u32_b32 v1, s8, 0
	v_mbcnt_hi_u32_b32 v1, s9, v1
	s_waitcnt lgkmcnt(0)
	global_load_dword v0, v2, s[4:5] offset:40
	v_cmp_eq_u32_e32 vcc, 0, v1
	s_and_saveexec_b64 s[10:11], vcc
	s_cbranch_execz .LBB0_96
	s_bcnt1_i32_b64 s2, s[8:9]
	v_mov_b32_e32 v3, s2
	global_atomic_add v3, v2, v3, s[4:5] offset:32 sc0

.LBB0_156:
	s_or_b64 exec, exec, s[0:1]
	s_mov_b32 s100, 0xf81
	s_add_u32 s99, s81, 0x100
	s_cmp_lt_u32 s81, 0x60
	s_cselect_b32 s99, s99, s81
	s_and_b32 s98, s81, 8
	s_cmp_eq_u32 s98, 0
	s_cbranch_scc1 .Lgrp_a
	s_mov_b32 s101, 2
	s_sub_u32 s0, s78, 0x160
	s_subb_u32 s1, s79, 0
	s_branch .Lp0_enter
.Lgrp_a:
	s_mov_b32 s101, 1
.Lp1_enter:
	s_cmpk_eq_i32 s82, 0x100
	s_cselect_b64 s[2:3], -1, 0
	s_cmpk_lg_i32 s82, 0x100
	s_cselect_b64 s[0:1], -1, 0
	v_writelane_b32 v240, s0, 11
	s_cmp_lt_i32 s81, 32
	v_lshrrev_b32_e32 v205, 6, v193
	v_writelane_b32 v240, s1, 12
	s_cselect_b64 s[0:1], -1, 0
	v_writelane_b32 v240, s2, 23
	v_and_b32_e32 v192, 63, v193
	v_mbcnt_lo_u32_b32 v207, -1, 0
	v_writelane_b32 v240, s3, 24
	s_and_b64 s[2:3], s[0:1], s[2:3]
	s_andn2_b64 vcc, exec, s[2:3]
	s_waitcnt lgkmcnt(0)
	s_barrier
	s_cbranch_vccnz .LBB0_168
	v_readfirstlane_b32 s3, v205
	v_lshlrev_b32_e32 v194, 4, v192
	v_lshlrev_b32_e32 v196, 3, v192
	v_mbcnt_hi_u32_b32 v197, -1, v207
	v_readlane_b32 s18, v241, 2
	v_readlane_b32 s19, v241, 3
	v_add_u32_e32 v195, 0x1000, v194
	v_xor_b32_e32 v198, 32, v197
	v_lshlrev_b32_e32 v198, 2, v198
	v_xor_b32_e32 v199, 16, v197
	v_lshlrev_b32_e32 v199, 2, v199
	v_xor_b32_e32 v200, 8, v197
	v_lshlrev_b32_e32 v200, 2, v200
	v_xor_b32_e32 v201, 4, v197
	v_lshlrev_b32_e32 v201, 2, v201
	v_xor_b32_e32 v202, 2, v197
	v_lshlrev_b32_e32 v202, 2, v202
	v_xor_b32_e32 v203, 1, v197
	v_lshlrev_b32_e32 v203, 2, v203
	v_mov_b32_e32 v208, 0x358637bd
	s_mov_b32 s27, 0x800000
	s_lshr_b32 s2, s81, 2
	s_lshl_b32 s2, s2, 8
	s_lshl_b32 s3, s3, 5
	s_add_u32 s2, s2, s3
	s_lshl_b32 s4, s2, 12
	s_add_u32 s14, s56, s4
	s_addc_u32 s15, s57, 0
	s_add_u32 s2, s2, 0x8000
	s_lshl_b32 s4, s2, 11
	s_add_u32 s10, s94, s4
	s_addc_u32 s11, s95, 0
	s_add_u32 s16, s18, 0x18000
	s_addc_u32 s17, s19, 0
	global_load_dwordx4 v[0:3], v194, s[60:61]
	global_load_dwordx4 v[4:7], v194, s[60:61] offset:1024
	global_load_dwordx4 v[8:11], v194, s[60:61] offset:2048
	global_load_dwordx4 v[12:15], v194, s[60:61] offset:3072
	global_load_dwordx4 v[160:163], v194, s[16:17]
	global_load_dwordx4 v[164:167], v194, s[16:17] offset:1024
	global_load_dwordx4 v[168:171], v194, s[16:17] offset:2048
	global_load_dwordx4 v[172:175], v194, s[16:17] offset:3072
	global_load_dwordx4 v[144:147], v195, s[16:17]
	global_load_dwordx4 v[148:151], v195, s[16:17] offset:1024
	global_load_dwordx4 v[152:155], v195, s[16:17] offset:2048
	global_load_dwordx4 v[156:159], v195, s[16:17] offset:3072
	global_load_dwordx4 v[16:19], v194, s[14:15]
	global_load_dwordx4 v[20:23], v194, s[14:15] offset:1024
	global_load_dwordx4 v[24:27], v194, s[14:15] offset:2048
	global_load_dwordx4 v[28:31], v194, s[14:15] offset:3072
	global_load_dwordx4 v[32:35], v195, s[14:15]
	global_load_dwordx4 v[36:39], v195, s[14:15] offset:1024
	global_load_dwordx4 v[40:43], v195, s[14:15] offset:2048
	global_load_dwordx4 v[44:47], v195, s[14:15] offset:3072
	s_add_u32 s14, s14, 0x2000
	s_addc_u32 s15, s15, 0
	global_load_dwordx4 v[48:51], v194, s[14:15]
	global_load_dwordx4 v[52:55], v194, s[14:15] offset:1024
	global_load_dwordx4 v[56:59], v194, s[14:15] offset:2048
	global_load_dwordx4 v[60:63], v194, s[14:15] offset:3072
	global_load_dwordx4 v[64:67], v195, s[14:15]
	global_load_dwordx4 v[68:71], v195, s[14:15] offset:1024
	global_load_dwordx4 v[72:75], v195, s[14:15] offset:2048
	global_load_dwordx4 v[76:79], v195, s[14:15] offset:3072
	s_add_u32 s14, s14, 0x2000
	s_addc_u32 s15, s15, 0
	global_load_dwordx4 v[80:83], v194, s[14:15]
	global_load_dwordx4 v[84:87], v194, s[14:15] offset:1024
	global_load_dwordx4 v[88:91], v194, s[14:15] offset:2048
	global_load_dwordx4 v[92:95], v194, s[14:15] offset:3072
	global_load_dwordx4 v[96:99], v195, s[14:15]
	global_load_dwordx4 v[100:103], v195, s[14:15] offset:1024
	global_load_dwordx4 v[104:107], v195, s[14:15] offset:2048
	global_load_dwordx4 v[108:111], v195, s[14:15] offset:3072
	s_add_u32 s14, s14, 0x2000
	s_addc_u32 s15, s15, 0
	global_load_dwordx4 v[112:115], v194, s[14:15]
	global_load_dwordx4 v[116:119], v194, s[14:15] offset:1024
	global_load_dwordx4 v[120:123], v194, s[14:15] offset:2048
	global_load_dwordx4 v[124:127], v194, s[14:15] offset:3072
	global_load_dwordx4 v[128:131], v195, s[14:15]
	global_load_dwordx4 v[132:135], v195, s[14:15] offset:1024
	global_load_dwordx4 v[136:139], v195, s[14:15] offset:2048
	global_load_dwordx4 v[140:143], v195, s[14:15] offset:3072
	s_waitcnt vmcnt(32)
	v_add_f32_e32 v144, 1.0, v144
	v_add_f32_e32 v145, 1.0, v145
	v_add_f32_e32 v146, 1.0, v146
	v_add_f32_e32 v147, 1.0, v147
	v_add_f32_e32 v148, 1.0, v148
	v_add_f32_e32 v149, 1.0, v149
	v_add_f32_e32 v150, 1.0, v150
	v_add_f32_e32 v151, 1.0, v151
	v_add_f32_e32 v152, 1.0, v152
	v_add_f32_e32 v153, 1.0, v153
	v_add_f32_e32 v154, 1.0, v154
	v_add_f32_e32 v155, 1.0, v155
	v_add_f32_e32 v156, 1.0, v156
	v_add_f32_e32 v157, 1.0, v157
	v_add_f32_e32 v158, 1.0, v158
	v_add_f32_e32 v159, 1.0, v159
	s_waitcnt vmcnt(24)
	v_pk_mul_f32 v[178:179], v[16:17], v[16:17]
	v_pk_fma_f32 v[178:179], v[18:19], v[18:19], v[178:179]
	v_pk_fma_f32 v[178:179], v[20:21], v[20:21], v[178:179]
	v_pk_fma_f32 v[178:179], v[22:23], v[22:23], v[178:179]
	v_pk_fma_f32 v[178:179], v[24:25], v[24:25], v[178:179]
	v_pk_fma_f32 v[178:179], v[26:27], v[26:27], v[178:179]
	v_pk_fma_f32 v[178:179], v[28:29], v[28:29], v[178:179]
	v_pk_fma_f32 v[178:179], v[30:31], v[30:31], v[178:179]
	v_pk_mul_f32 v[180:181], v[32:33], v[32:33]
	v_pk_fma_f32 v[180:181], v[34:35], v[34:35], v[180:181]
	v_pk_fma_f32 v[180:181], v[36:37], v[36:37], v[180:181]
	v_pk_fma_f32 v[180:181], v[38:39], v[38:39], v[180:181]
	v_pk_fma_f32 v[180:181], v[40:41], v[40:41], v[180:181]
	v_pk_fma_f32 v[180:181], v[42:43], v[42:43], v[180:181]
	v_pk_fma_f32 v[180:181], v[44:45], v[44:45], v[180:181]
	v_pk_fma_f32 v[180:181], v[46:47], v[46:47], v[180:181]
	v_add_f32_e32 v176, v178, v179
	v_add_f32_e32 v177, v180, v181
	ds_bpermute_b32 v178, v198, v176
	ds_bpermute_b32 v179, v198, v177
	s_waitcnt lgkmcnt(0)
	v_add_f32_e32 v176, v176, v178
	v_add_f32_e32 v177, v177, v179
	ds_bpermute_b32 v178, v199, v176
	ds_bpermute_b32 v179, v199, v177
	s_waitcnt lgkmcnt(0)
	v_add_f32_e32 v176, v176, v178
	v_add_f32_e32 v177, v177, v179
	ds_bpermute_b32 v178, v200, v176
	ds_bpermute_b32 v179, v200, v177
	s_waitcnt lgkmcnt(0)
	v_add_f32_e32 v176, v176, v178
	v_add_f32_e32 v177, v177, v179
	ds_bpermute_b32 v178, v201, v176
	ds_bpermute_b32 v179, v201, v177
	s_waitcnt lgkmcnt(0)
	v_add_f32_e32 v176, v176, v178
	v_add_f32_e32 v177, v177, v179
	ds_bpermute_b32 v178, v202, v176
	ds_bpermute_b32 v179, v202, v177
	s_waitcnt lgkmcnt(0)
	v_add_f32_e32 v176, v176, v178
	v_add_f32_e32 v177, v177, v179
	ds_bpermute_b32 v178, v203, v176
	ds_bpermute_b32 v179, v203, v177
	s_waitcnt lgkmcnt(0)
	v_add_f32_e32 v176, v176, v178
	v_add_f32_e32 v177, v177, v179
	v_fmamk_f32 v176, v176, 0x3a800000, v208
	v_mul_f32_e32 v178, 0x4b800000, v176
	v_cmp_gt_f32_e32 vcc, s27, v176
	s_nop 1
	v_cndmask_b32_e32 v176, v176, v178, vcc
	v_rsq_f32_e32 v209, v176
	s_nop 0
	v_mul_f32_e32 v178, 0x45800000, v209
	v_cndmask_b32_e32 v209, v209, v178, vcc
	v_fmamk_f32 v177, v177, 0x3a800000, v208
	v_mul_f32_e32 v178, 0x4b800000, v177
	v_cmp_gt_f32_e32 vcc, s27, v177
	s_nop 1
	v_cndmask_b32_e32 v177, v177, v178, vcc
	v_rsq_f32_e32 v210, v177
	s_nop 0
	v_mul_f32_e32 v178, 0x45800000, v210
	v_cndmask_b32_e32 v210, v210, v178, vcc
	v_mul_f32_e32 v16, v16, v209
	v_mul_f32_e32 v16, v0, v16
	v_fma_f32 v16, v144, v16, v160
	v_mul_f32_e32 v17, v17, v209
	v_mul_f32_e32 v17, v1, v17
	v_fma_f32 v17, v145, v17, v161
	v_mul_f32_e32 v18, v18, v209
	v_mul_f32_e32 v18, v2, v18
	v_fma_f32 v18, v146, v18, v162
	v_mul_f32_e32 v19, v19, v209
	v_mul_f32_e32 v19, v3, v19
	v_fma_f32 v19, v147, v19, v163
	v_cvt_pk_bf16_f32 v180, v16, v17
	v_cvt_pk_bf16_f32 v181, v18, v19
	global_store_dwordx2 v196, v[180:181], s[10:11]
	s_nop 0
	v_mul_f32_e32 v20, v20, v209
	v_mul_f32_e32 v20, v4, v20
	v_fma_f32 v20, v148, v20, v164
	v_mul_f32_e32 v21, v21, v209
	v_mul_f32_e32 v21, v5, v21
	v_fma_f32 v21, v149, v21, v165
	v_mul_f32_e32 v22, v22, v209
	v_mul_f32_e32 v22, v6, v22
	v_fma_f32 v22, v150, v22, v166
	v_mul_f32_e32 v23, v23, v209
	v_mul_f32_e32 v23, v7, v23
	v_fma_f32 v23, v151, v23, v167
	v_cvt_pk_bf16_f32 v180, v20, v21
	v_cvt_pk_bf16_f32 v181, v22, v23
	global_store_dwordx2 v196, v[180:181], s[10:11] offset:512
	s_nop 0
	v_mul_f32_e32 v24, v24, v209
	v_mul_f32_e32 v24, v8, v24
	v_fma_f32 v24, v152, v24, v168
	v_mul_f32_e32 v25, v25, v209
	v_mul_f32_e32 v25, v9, v25
	v_fma_f32 v25, v153, v25, v169
	v_mul_f32_e32 v26, v26, v209
	v_mul_f32_e32 v26, v10, v26
	v_fma_f32 v26, v154, v26, v170
	v_mul_f32_e32 v27, v27, v209
	v_mul_f32_e32 v27, v11, v27
	v_fma_f32 v27, v155, v27, v171
	v_cvt_pk_bf16_f32 v180, v24, v25
	v_cvt_pk_bf16_f32 v181, v26, v27
	global_store_dwordx2 v196, v[180:181], s[10:11] offset:1024
	s_nop 0
	v_mul_f32_e32 v28, v28, v209
	v_mul_f32_e32 v28, v12, v28
	v_fma_f32 v28, v156, v28, v172
	v_mul_f32_e32 v29, v29, v209
	v_mul_f32_e32 v29, v13, v29
	v_fma_f32 v29, v157, v29, v173
	v_mul_f32_e32 v30, v30, v209
	v_mul_f32_e32 v30, v14, v30
	v_fma_f32 v30, v158, v30, v174
	v_mul_f32_e32 v31, v31, v209
	v_mul_f32_e32 v31, v15, v31
	v_fma_f32 v31, v159, v31, v175
	v_cvt_pk_bf16_f32 v180, v28, v29
	v_cvt_pk_bf16_f32 v181, v30, v31
	global_store_dwordx2 v196, v[180:181], s[10:11] offset:1536
	s_nop 0
	v_mul_f32_e32 v32, v32, v210
	v_mul_f32_e32 v32, v0, v32
	v_fma_f32 v32, v144, v32, v160
	v_mul_f32_e32 v33, v33, v210
	v_mul_f32_e32 v33, v1, v33
	v_fma_f32 v33, v145, v33, v161
	v_mul_f32_e32 v34, v34, v210
	v_mul_f32_e32 v34, v2, v34
	v_fma_f32 v34, v146, v34, v162
	v_mul_f32_e32 v35, v35, v210
	v_mul_f32_e32 v35, v3, v35
	v_fma_f32 v35, v147, v35, v163
	v_cvt_pk_bf16_f32 v180, v32, v33
	v_cvt_pk_bf16_f32 v181, v34, v35
	global_store_dwordx2 v196, v[180:181], s[10:11] offset:2048
	s_nop 0
	v_mul_f32_e32 v36, v36, v210
	v_mul_f32_e32 v36, v4, v36
	v_fma_f32 v36, v148, v36, v164
	v_mul_f32_e32 v37, v37, v210
	v_mul_f32_e32 v37, v5, v37
	v_fma_f32 v37, v149, v37, v165
	v_mul_f32_e32 v38, v38, v210
	v_mul_f32_e32 v38, v6, v38
	v_fma_f32 v38, v150, v38, v166
	v_mul_f32_e32 v39, v39, v210
	v_mul_f32_e32 v39, v7, v39
	v_fma_f32 v39, v151, v39, v167
	v_cvt_pk_bf16_f32 v180, v36, v37
	v_cvt_pk_bf16_f32 v181, v38, v39
	global_store_dwordx2 v196, v[180:181], s[10:11] offset:2560
	s_nop 0
	v_mul_f32_e32 v40, v40, v210
	v_mul_f32_e32 v40, v8, v40
	v_fma_f32 v40, v152, v40, v168
	v_mul_f32_e32 v41, v41, v210
	v_mul_f32_e32 v41, v9, v41
	v_fma_f32 v41, v153, v41, v169
	v_mul_f32_e32 v42, v42, v210
	v_mul_f32_e32 v42, v10, v42
	v_fma_f32 v42, v154, v42, v170
	v_mul_f32_e32 v43, v43, v210
	v_mul_f32_e32 v43, v11, v43
	v_fma_f32 v43, v155, v43, v171
	v_cvt_pk_bf16_f32 v180, v40, v41
	v_cvt_pk_bf16_f32 v181, v42, v43
	global_store_dwordx2 v196, v[180:181], s[10:11] offset:3072
	s_nop 0
	v_mul_f32_e32 v44, v44, v210
	v_mul_f32_e32 v44, v12, v44
	v_fma_f32 v44, v156, v44, v172
	v_mul_f32_e32 v45, v45, v210
	v_mul_f32_e32 v45, v13, v45
	v_fma_f32 v45, v157, v45, v173
	v_mul_f32_e32 v46, v46, v210
	v_mul_f32_e32 v46, v14, v46
	v_fma_f32 v46, v158, v46, v174
	v_mul_f32_e32 v47, v47, v210
	v_mul_f32_e32 v47, v15, v47
	v_fma_f32 v47, v159, v47, v175
	v_cvt_pk_bf16_f32 v180, v44, v45
	v_cvt_pk_bf16_f32 v181, v46, v47
	global_store_dwordx2 v196, v[180:181], s[10:11] offset:3584
	s_nop 0
	s_add_u32 s14, s14, 0x2000
	s_addc_u32 s15, s15, 0
	global_load_dwordx4 v[16:19], v194, s[14:15]
	global_load_dwordx4 v[20:23], v194, s[14:15] offset:1024
	global_load_dwordx4 v[24:27], v194, s[14:15] offset:2048
	global_load_dwordx4 v[28:31], v194, s[14:15] offset:3072
	global_load_dwordx4 v[32:35], v195, s[14:15]
	global_load_dwordx4 v[36:39], v195, s[14:15] offset:1024
	global_load_dwordx4 v[40:43], v195, s[14:15] offset:2048
	global_load_dwordx4 v[44:47], v195, s[14:15] offset:3072
	s_waitcnt vmcnt(32)
	v_pk_mul_f32 v[178:179], v[48:49], v[48:49]
	v_pk_fma_f32 v[178:179], v[50:51], v[50:51], v[178:179]
	v_pk_fma_f32 v[178:179], v[52:53], v[52:53], v[178:179]
	v_pk_fma_f32 v[178:179], v[54:55], v[54:55], v[178:179]
	v_pk_fma_f32 v[178:179], v[56:57], v[56:57], v[178:179]
	v_pk_fma_f32 v[178:179], v[58:59], v[58:59], v[178:179]
	v_pk_fma_f32 v[178:179], v[60:61], v[60:61], v[178:179]
	v_pk_fma_f32 v[178:179], v[62:63], v[62:63], v[178:179]
	v_pk_mul_f32 v[180:181], v[64:65], v[64:65]
	v_pk_fma_f32 v[180:181], v[66:67], v[66:67], v[180:181]
	v_pk_fma_f32 v[180:181], v[68:69], v[68:69], v[180:181]
	v_pk_fma_f32 v[180:181], v[70:71], v[70:71], v[180:181]
	v_pk_fma_f32 v[180:181], v[72:73], v[72:73], v[180:181]
	v_pk_fma_f32 v[180:181], v[74:75], v[74:75], v[180:181]
	v_pk_fma_f32 v[180:181], v[76:77], v[76:77], v[180:181]
	v_pk_fma_f32 v[180:181], v[78:79], v[78:79], v[180:181]
	v_add_f32_e32 v176, v178, v179
	v_add_f32_e32 v177, v180, v181
	ds_bpermute_b32 v178, v198, v176
	ds_bpermute_b32 v179, v198, v177
	s_waitcnt lgkmcnt(0)
	v_add_f32_e32 v176, v176, v178
	v_add_f32_e32 v177, v177, v179
	ds_bpermute_b32 v178, v199, v176
	ds_bpermute_b32 v179, v199, v177
	s_waitcnt lgkmcnt(0)
	v_add_f32_e32 v176, v176, v178
	v_add_f32_e32 v177, v177, v179
	ds_bpermute_b32 v178, v200, v176
	ds_bpermute_b32 v179, v200, v177
	s_waitcnt lgkmcnt(0)
	v_add_f32_e32 v176, v176, v178
	v_add_f32_e32 v177, v177, v179
	ds_bpermute_b32 v178, v201, v176
	ds_bpermute_b32 v179, v201, v177
	s_waitcnt lgkmcnt(0)
	v_add_f32_e32 v176, v176, v178
	v_add_f32_e32 v177, v177, v179
	ds_bpermute_b32 v178, v202, v176
	ds_bpermute_b32 v179, v202, v177
	s_waitcnt lgkmcnt(0)
	v_add_f32_e32 v176, v176, v178
	v_add_f32_e32 v177, v177, v179
	ds_bpermute_b32 v178, v203, v176
	ds_bpermute_b32 v179, v203, v177
	s_waitcnt lgkmcnt(0)
	v_add_f32_e32 v176, v176, v178
	v_add_f32_e32 v177, v177, v179
	v_fmamk_f32 v176, v176, 0x3a800000, v208
	v_mul_f32_e32 v178, 0x4b800000, v176
	v_cmp_gt_f32_e32 vcc, s27, v176
	s_nop 1
	v_cndmask_b32_e32 v176, v176, v178, vcc
	v_rsq_f32_e32 v209, v176
	s_nop 0
	v_mul_f32_e32 v178, 0x45800000, v209
	v_cndmask_b32_e32 v209, v209, v178, vcc
	v_fmamk_f32 v177, v177, 0x3a800000, v208
	v_mul_f32_e32 v178, 0x4b800000, v177
	v_cmp_gt_f32_e32 vcc, s27, v177
	s_nop 1
	v_cndmask_b32_e32 v177, v177, v178, vcc
	v_rsq_f32_e32 v210, v177
	s_nop 0
	v_mul_f32_e32 v178, 0x45800000, v210
	v_cndmask_b32_e32 v210, v210, v178, vcc
	s_add_u32 s10, s10, 0x1000
	s_addc_u32 s11, s11, 0
	v_mul_f32_e32 v48, v48, v209
	v_mul_f32_e32 v48, v0, v48
	v_fma_f32 v48, v144, v48, v160
	v_mul_f32_e32 v49, v49, v209
	v_mul_f32_e32 v49, v1, v49
	v_fma_f32 v49, v145, v49, v161
	v_mul_f32_e32 v50, v50, v209
	v_mul_f32_e32 v50, v2, v50
	v_fma_f32 v50, v146, v50, v162
	v_mul_f32_e32 v51, v51, v209
	v_mul_f32_e32 v51, v3, v51
	v_fma_f32 v51, v147, v51, v163
	v_cvt_pk_bf16_f32 v180, v48, v49
	v_cvt_pk_bf16_f32 v181, v50, v51
	global_store_dwordx2 v196, v[180:181], s[10:11]
	s_nop 0
	v_mul_f32_e32 v52, v52, v209
	v_mul_f32_e32 v52, v4, v52
	v_fma_f32 v52, v148, v52, v164
	v_mul_f32_e32 v53, v53, v209
	v_mul_f32_e32 v53, v5, v53
	v_fma_f32 v53, v149, v53, v165
	v_mul_f32_e32 v54, v54, v209
	v_mul_f32_e32 v54, v6, v54
	v_fma_f32 v54, v150, v54, v166
	v_mul_f32_e32 v55, v55, v209
	v_mul_f32_e32 v55, v7, v55
	v_fma_f32 v55, v151, v55, v167
	v_cvt_pk_bf16_f32 v180, v52, v53
	v_cvt_pk_bf16_f32 v181, v54, v55
	global_store_dwordx2 v196, v[180:181], s[10:11] offset:512
	s_nop 0
	v_mul_f32_e32 v56, v56, v209
	v_mul_f32_e32 v56, v8, v56
	v_fma_f32 v56, v152, v56, v168
	v_mul_f32_e32 v57, v57, v209
	v_mul_f32_e32 v57, v9, v57
	v_fma_f32 v57, v153, v57, v169
	v_mul_f32_e32 v58, v58, v209
	v_mul_f32_e32 v58, v10, v58
	v_fma_f32 v58, v154, v58, v170
	v_mul_f32_e32 v59, v59, v209
	v_mul_f32_e32 v59, v11, v59
	v_fma_f32 v59, v155, v59, v171
	v_cvt_pk_bf16_f32 v180, v56, v57
	v_cvt_pk_bf16_f32 v181, v58, v59
	global_store_dwordx2 v196, v[180:181], s[10:11] offset:1024
	s_nop 0
	v_mul_f32_e32 v60, v60, v209
	v_mul_f32_e32 v60, v12, v60
	v_fma_f32 v60, v156, v60, v172
	v_mul_f32_e32 v61, v61, v209
	v_mul_f32_e32 v61, v13, v61
	v_fma_f32 v61, v157, v61, v173
	v_mul_f32_e32 v62, v62, v209
	v_mul_f32_e32 v62, v14, v62
	v_fma_f32 v62, v158, v62, v174
	v_mul_f32_e32 v63, v63, v209
	v_mul_f32_e32 v63, v15, v63
	v_fma_f32 v63, v159, v63, v175
	v_cvt_pk_bf16_f32 v180, v60, v61
	v_cvt_pk_bf16_f32 v181, v62, v63
	global_store_dwordx2 v196, v[180:181], s[10:11] offset:1536
	s_nop 0
	v_mul_f32_e32 v64, v64, v210
	v_mul_f32_e32 v64, v0, v64
	v_fma_f32 v64, v144, v64, v160
	v_mul_f32_e32 v65, v65, v210
	v_mul_f32_e32 v65, v1, v65
	v_fma_f32 v65, v145, v65, v161
	v_mul_f32_e32 v66, v66, v210
	v_mul_f32_e32 v66, v2, v66
	v_fma_f32 v66, v146, v66, v162
	v_mul_f32_e32 v67, v67, v210
	v_mul_f32_e32 v67, v3, v67
	v_fma_f32 v67, v147, v67, v163
	v_cvt_pk_bf16_f32 v180, v64, v65
	v_cvt_pk_bf16_f32 v181, v66, v67
	global_store_dwordx2 v196, v[180:181], s[10:11] offset:2048
	s_nop 0
	v_mul_f32_e32 v68, v68, v210
	v_mul_f32_e32 v68, v4, v68
	v_fma_f32 v68, v148, v68, v164
	v_mul_f32_e32 v69, v69, v210
	v_mul_f32_e32 v69, v5, v69
	v_fma_f32 v69, v149, v69, v165
	v_mul_f32_e32 v70, v70, v210
	v_mul_f32_e32 v70, v6, v70
	v_fma_f32 v70, v150, v70, v166
	v_mul_f32_e32 v71, v71, v210
	v_mul_f32_e32 v71, v7, v71
	v_fma_f32 v71, v151, v71, v167
	v_cvt_pk_bf16_f32 v180, v68, v69
	v_cvt_pk_bf16_f32 v181, v70, v71
	global_store_dwordx2 v196, v[180:181], s[10:11] offset:2560
	s_nop 0
	v_mul_f32_e32 v72, v72, v210
	v_mul_f32_e32 v72, v8, v72
	v_fma_f32 v72, v152, v72, v168
	v_mul_f32_e32 v73, v73, v210
	v_mul_f32_e32 v73, v9, v73
	v_fma_f32 v73, v153, v73, v169
	v_mul_f32_e32 v74, v74, v210
	v_mul_f32_e32 v74, v10, v74
	v_fma_f32 v74, v154, v74, v170
	v_mul_f32_e32 v75, v75, v210
	v_mul_f32_e32 v75, v11, v75
	v_fma_f32 v75, v155, v75, v171
	v_cvt_pk_bf16_f32 v180, v72, v73
	v_cvt_pk_bf16_f32 v181, v74, v75
	global_store_dwordx2 v196, v[180:181], s[10:11] offset:3072
	s_nop 0
	v_mul_f32_e32 v76, v76, v210
	v_mul_f32_e32 v76, v12, v76
	v_fma_f32 v76, v156, v76, v172
	v_mul_f32_e32 v77, v77, v210
	v_mul_f32_e32 v77, v13, v77
	v_fma_f32 v77, v157, v77, v173
	v_mul_f32_e32 v78, v78, v210
	v_mul_f32_e32 v78, v14, v78
	v_fma_f32 v78, v158, v78, v174
	v_mul_f32_e32 v79, v79, v210
	v_mul_f32_e32 v79, v15, v79
	v_fma_f32 v79, v159, v79, v175
	v_cvt_pk_bf16_f32 v180, v76, v77
	v_cvt_pk_bf16_f32 v181, v78, v79
	global_store_dwordx2 v196, v[180:181], s[10:11] offset:3584
	s_nop 0
	s_add_u32 s14, s14, 0x2000
	s_addc_u32 s15, s15, 0
	global_load_dwordx4 v[48:51], v194, s[14:15]
	global_load_dwordx4 v[52:55], v194, s[14:15] offset:1024
	global_load_dwordx4 v[56:59], v194, s[14:15] offset:2048
	global_load_dwordx4 v[60:63], v194, s[14:15] offset:3072
	global_load_dwordx4 v[64:67], v195, s[14:15]
	global_load_dwordx4 v[68:71], v195, s[14:15] offset:1024
	global_load_dwordx4 v[72:75], v195, s[14:15] offset:2048
	global_load_dwordx4 v[76:79], v195, s[14:15] offset:3072
	s_waitcnt vmcnt(40)
	v_pk_mul_f32 v[178:179], v[80:81], v[80:81]
	v_pk_fma_f32 v[178:179], v[82:83], v[82:83], v[178:179]
	v_pk_fma_f32 v[178:179], v[84:85], v[84:85], v[178:179]
	v_pk_fma_f32 v[178:179], v[86:87], v[86:87], v[178:179]
	v_pk_fma_f32 v[178:179], v[88:89], v[88:89], v[178:179]
	v_pk_fma_f32 v[178:179], v[90:91], v[90:91], v[178:179]
	v_pk_fma_f32 v[178:179], v[92:93], v[92:93], v[178:179]
	v_pk_fma_f32 v[178:179], v[94:95], v[94:95], v[178:179]
	v_pk_mul_f32 v[180:181], v[96:97], v[96:97]
	v_pk_fma_f32 v[180:181], v[98:99], v[98:99], v[180:181]
	v_pk_fma_f32 v[180:181], v[100:101], v[100:101], v[180:181]
	v_pk_fma_f32 v[180:181], v[102:103], v[102:103], v[180:181]
	v_pk_fma_f32 v[180:181], v[104:105], v[104:105], v[180:181]
	v_pk_fma_f32 v[180:181], v[106:107], v[106:107], v[180:181]
	v_pk_fma_f32 v[180:181], v[108:109], v[108:109], v[180:181]
	v_pk_fma_f32 v[180:181], v[110:111], v[110:111], v[180:181]
	v_add_f32_e32 v176, v178, v179
	v_add_f32_e32 v177, v180, v181
	ds_bpermute_b32 v178, v198, v176
	ds_bpermute_b32 v179, v198, v177
	s_waitcnt lgkmcnt(0)
	v_add_f32_e32 v176, v176, v178
	v_add_f32_e32 v177, v177, v179
	ds_bpermute_b32 v178, v199, v176
	ds_bpermute_b32 v179, v199, v177
	s_waitcnt lgkmcnt(0)
	v_add_f32_e32 v176, v176, v178
	v_add_f32_e32 v177, v177, v179
	ds_bpermute_b32 v178, v200, v176
	ds_bpermute_b32 v179, v200, v177
	s_waitcnt lgkmcnt(0)
	v_add_f32_e32 v176, v176, v178
	v_add_f32_e32 v177, v177, v179
	ds_bpermute_b32 v178, v201, v176
	ds_bpermute_b32 v179, v201, v177
	s_waitcnt lgkmcnt(0)
	v_add_f32_e32 v176, v176, v178
	v_add_f32_e32 v177, v177, v179
	ds_bpermute_b32 v178, v202, v176
	ds_bpermute_b32 v179, v202, v177
	s_waitcnt lgkmcnt(0)
	v_add_f32_e32 v176, v176, v178
	v_add_f32_e32 v177, v177, v179
	ds_bpermute_b32 v178, v203, v176
	ds_bpermute_b32 v179, v203, v177
	s_waitcnt lgkmcnt(0)
	v_add_f32_e32 v176, v176, v178
	v_add_f32_e32 v177, v177, v179
	v_fmamk_f32 v176, v176, 0x3a800000, v208
	v_mul_f32_e32 v178, 0x4b800000, v176
	v_cmp_gt_f32_e32 vcc, s27, v176
	s_nop 1
	v_cndmask_b32_e32 v176, v176, v178, vcc
	v_rsq_f32_e32 v209, v176
	s_nop 0
	v_mul_f32_e32 v178, 0x45800000, v209
	v_cndmask_b32_e32 v209, v209, v178, vcc
	v_fmamk_f32 v177, v177, 0x3a800000, v208
	v_mul_f32_e32 v178, 0x4b800000, v177
	v_cmp_gt_f32_e32 vcc, s27, v177
	s_nop 1
	v_cndmask_b32_e32 v177, v177, v178, vcc
	v_rsq_f32_e32 v210, v177
	s_nop 0
	v_mul_f32_e32 v178, 0x45800000, v210
	v_cndmask_b32_e32 v210, v210, v178, vcc
	s_add_u32 s10, s10, 0x1000
	s_addc_u32 s11, s11, 0
	v_mul_f32_e32 v80, v80, v209
	v_mul_f32_e32 v80, v0, v80
	v_fma_f32 v80, v144, v80, v160
	v_mul_f32_e32 v81, v81, v209
	v_mul_f32_e32 v81, v1, v81
	v_fma_f32 v81, v145, v81, v161
	v_mul_f32_e32 v82, v82, v209
	v_mul_f32_e32 v82, v2, v82
	v_fma_f32 v82, v146, v82, v162
	v_mul_f32_e32 v83, v83, v209
	v_mul_f32_e32 v83, v3, v83
	v_fma_f32 v83, v147, v83, v163
	v_cvt_pk_bf16_f32 v180, v80, v81
	v_cvt_pk_bf16_f32 v181, v82, v83
	global_store_dwordx2 v196, v[180:181], s[10:11]
	s_nop 0
	v_mul_f32_e32 v84, v84, v209
	v_mul_f32_e32 v84, v4, v84
	v_fma_f32 v84, v148, v84, v164
	v_mul_f32_e32 v85, v85, v209
	v_mul_f32_e32 v85, v5, v85
	v_fma_f32 v85, v149, v85, v165
	v_mul_f32_e32 v86, v86, v209
	v_mul_f32_e32 v86, v6, v86
	v_fma_f32 v86, v150, v86, v166
	v_mul_f32_e32 v87, v87, v209
	v_mul_f32_e32 v87, v7, v87
	v_fma_f32 v87, v151, v87, v167
	v_cvt_pk_bf16_f32 v180, v84, v85
	v_cvt_pk_bf16_f32 v181, v86, v87
	global_store_dwordx2 v196, v[180:181], s[10:11] offset:512
	s_nop 0
	v_mul_f32_e32 v88, v88, v209
	v_mul_f32_e32 v88, v8, v88
	v_fma_f32 v88, v152, v88, v168
	v_mul_f32_e32 v89, v89, v209
	v_mul_f32_e32 v89, v9, v89
	v_fma_f32 v89, v153, v89, v169
	v_mul_f32_e32 v90, v90, v209
	v_mul_f32_e32 v90, v10, v90
	v_fma_f32 v90, v154, v90, v170
	v_mul_f32_e32 v91, v91, v209
	v_mul_f32_e32 v91, v11, v91
	v_fma_f32 v91, v155, v91, v171
	v_cvt_pk_bf16_f32 v180, v88, v89
	v_cvt_pk_bf16_f32 v181, v90, v91
	global_store_dwordx2 v196, v[180:181], s[10:11] offset:1024
	s_nop 0
	v_mul_f32_e32 v92, v92, v209
	v_mul_f32_e32 v92, v12, v92
	v_fma_f32 v92, v156, v92, v172
	v_mul_f32_e32 v93, v93, v209
	v_mul_f32_e32 v93, v13, v93
	v_fma_f32 v93, v157, v93, v173
	v_mul_f32_e32 v94, v94, v209
	v_mul_f32_e32 v94, v14, v94
	v_fma_f32 v94, v158, v94, v174
	v_mul_f32_e32 v95, v95, v209
	v_mul_f32_e32 v95, v15, v95
	v_fma_f32 v95, v159, v95, v175
	v_cvt_pk_bf16_f32 v180, v92, v93
	v_cvt_pk_bf16_f32 v181, v94, v95
	global_store_dwordx2 v196, v[180:181], s[10:11] offset:1536
	s_nop 0
	v_mul_f32_e32 v96, v96, v210
	v_mul_f32_e32 v96, v0, v96
	v_fma_f32 v96, v144, v96, v160
	v_mul_f32_e32 v97, v97, v210
	v_mul_f32_e32 v97, v1, v97
	v_fma_f32 v97, v145, v97, v161
	v_mul_f32_e32 v98, v98, v210
	v_mul_f32_e32 v98, v2, v98
	v_fma_f32 v98, v146, v98, v162
	v_mul_f32_e32 v99, v99, v210
	v_mul_f32_e32 v99, v3, v99
	v_fma_f32 v99, v147, v99, v163
	v_cvt_pk_bf16_f32 v180, v96, v97
	v_cvt_pk_bf16_f32 v181, v98, v99
	global_store_dwordx2 v196, v[180:181], s[10:11] offset:2048
	s_nop 0
	v_mul_f32_e32 v100, v100, v210
	v_mul_f32_e32 v100, v4, v100
	v_fma_f32 v100, v148, v100, v164
	v_mul_f32_e32 v101, v101, v210
	v_mul_f32_e32 v101, v5, v101
	v_fma_f32 v101, v149, v101, v165
	v_mul_f32_e32 v102, v102, v210
	v_mul_f32_e32 v102, v6, v102
	v_fma_f32 v102, v150, v102, v166
	v_mul_f32_e32 v103, v103, v210
	v_mul_f32_e32 v103, v7, v103
	v_fma_f32 v103, v151, v103, v167
	v_cvt_pk_bf16_f32 v180, v100, v101
	v_cvt_pk_bf16_f32 v181, v102, v103
	global_store_dwordx2 v196, v[180:181], s[10:11] offset:2560
	s_nop 0
	v_mul_f32_e32 v104, v104, v210
	v_mul_f32_e32 v104, v8, v104
	v_fma_f32 v104, v152, v104, v168
	v_mul_f32_e32 v105, v105, v210
	v_mul_f32_e32 v105, v9, v105
	v_fma_f32 v105, v153, v105, v169
	v_mul_f32_e32 v106, v106, v210
	v_mul_f32_e32 v106, v10, v106
	v_fma_f32 v106, v154, v106, v170
	v_mul_f32_e32 v107, v107, v210
	v_mul_f32_e32 v107, v11, v107
	v_fma_f32 v107, v155, v107, v171
	v_cvt_pk_bf16_f32 v180, v104, v105
	v_cvt_pk_bf16_f32 v181, v106, v107
	global_store_dwordx2 v196, v[180:181], s[10:11] offset:3072
	s_nop 0
	v_mul_f32_e32 v108, v108, v210
	v_mul_f32_e32 v108, v12, v108
	v_fma_f32 v108, v156, v108, v172
	v_mul_f32_e32 v109, v109, v210
	v_mul_f32_e32 v109, v13, v109
	v_fma_f32 v109, v157, v109, v173
	v_mul_f32_e32 v110, v110, v210
	v_mul_f32_e32 v110, v14, v110
	v_fma_f32 v110, v158, v110, v174
	v_mul_f32_e32 v111, v111, v210
	v_mul_f32_e32 v111, v15, v111
	v_fma_f32 v111, v159, v111, v175
	v_cvt_pk_bf16_f32 v180, v108, v109
	v_cvt_pk_bf16_f32 v181, v110, v111
	global_store_dwordx2 v196, v[180:181], s[10:11] offset:3584
	s_nop 0
	s_add_u32 s14, s14, 0x2000
	s_addc_u32 s15, s15, 0
	global_load_dwordx4 v[80:83], v194, s[14:15]
	global_load_dwordx4 v[84:87], v194, s[14:15] offset:1024
	global_load_dwordx4 v[88:91], v194, s[14:15] offset:2048
	global_load_dwordx4 v[92:95], v194, s[14:15] offset:3072
	global_load_dwordx4 v[96:99], v195, s[14:15]
	global_load_dwordx4 v[100:103], v195, s[14:15] offset:1024
	global_load_dwordx4 v[104:107], v195, s[14:15] offset:2048
	global_load_dwordx4 v[108:111], v195, s[14:15] offset:3072
	s_waitcnt vmcnt(48)
	v_pk_mul_f32 v[178:179], v[112:113], v[112:113]
	v_pk_fma_f32 v[178:179], v[114:115], v[114:115], v[178:179]
	v_pk_fma_f32 v[178:179], v[116:117], v[116:117], v[178:179]
	v_pk_fma_f32 v[178:179], v[118:119], v[118:119], v[178:179]
	v_pk_fma_f32 v[178:179], v[120:121], v[120:121], v[178:179]
	v_pk_fma_f32 v[178:179], v[122:123], v[122:123], v[178:179]
	v_pk_fma_f32 v[178:179], v[124:125], v[124:125], v[178:179]
	v_pk_fma_f32 v[178:179], v[126:127], v[126:127], v[178:179]
	v_pk_mul_f32 v[180:181], v[128:129], v[128:129]
	v_pk_fma_f32 v[180:181], v[130:131], v[130:131], v[180:181]
	v_pk_fma_f32 v[180:181], v[132:133], v[132:133], v[180:181]
	v_pk_fma_f32 v[180:181], v[134:135], v[134:135], v[180:181]
	v_pk_fma_f32 v[180:181], v[136:137], v[136:137], v[180:181]
	v_pk_fma_f32 v[180:181], v[138:139], v[138:139], v[180:181]
	v_pk_fma_f32 v[180:181], v[140:141], v[140:141], v[180:181]
	v_pk_fma_f32 v[180:181], v[142:143], v[142:143], v[180:181]
	v_add_f32_e32 v176, v178, v179
	v_add_f32_e32 v177, v180, v181
	ds_bpermute_b32 v178, v198, v176
	ds_bpermute_b32 v179, v198, v177
	s_waitcnt lgkmcnt(0)
	v_add_f32_e32 v176, v176, v178
	v_add_f32_e32 v177, v177, v179
	ds_bpermute_b32 v178, v199, v176
	ds_bpermute_b32 v179, v199, v177
	s_waitcnt lgkmcnt(0)
	v_add_f32_e32 v176, v176, v178
	v_add_f32_e32 v177, v177, v179
	ds_bpermute_b32 v178, v200, v176
	ds_bpermute_b32 v179, v200, v177
	s_waitcnt lgkmcnt(0)
	v_add_f32_e32 v176, v176, v178
	v_add_f32_e32 v177, v177, v179
	ds_bpermute_b32 v178, v201, v176
	ds_bpermute_b32 v179, v201, v177
	s_waitcnt lgkmcnt(0)
	v_add_f32_e32 v176, v176, v178
	v_add_f32_e32 v177, v177, v179
	ds_bpermute_b32 v178, v202, v176
	ds_bpermute_b32 v179, v202, v177
	s_waitcnt lgkmcnt(0)
	v_add_f32_e32 v176, v176, v178
	v_add_f32_e32 v177, v177, v179
	ds_bpermute_b32 v178, v203, v176
	ds_bpermute_b32 v179, v203, v177
	s_waitcnt lgkmcnt(0)
	v_add_f32_e32 v176, v176, v178
	v_add_f32_e32 v177, v177, v179
	v_fmamk_f32 v176, v176, 0x3a800000, v208
	v_mul_f32_e32 v178, 0x4b800000, v176
	v_cmp_gt_f32_e32 vcc, s27, v176
	s_nop 1
	v_cndmask_b32_e32 v176, v176, v178, vcc
	v_rsq_f32_e32 v209, v176
	s_nop 0
	v_mul_f32_e32 v178, 0x45800000, v209
	v_cndmask_b32_e32 v209, v209, v178, vcc
	v_fmamk_f32 v177, v177, 0x3a800000, v208
	v_mul_f32_e32 v178, 0x4b800000, v177
	v_cmp_gt_f32_e32 vcc, s27, v177
	s_nop 1
	v_cndmask_b32_e32 v177, v177, v178, vcc
	v_rsq_f32_e32 v210, v177
	s_nop 0
	v_mul_f32_e32 v178, 0x45800000, v210
	v_cndmask_b32_e32 v210, v210, v178, vcc
	s_add_u32 s10, s10, 0x1000
	s_addc_u32 s11, s11, 0
	v_mul_f32_e32 v112, v112, v209
	v_mul_f32_e32 v112, v0, v112
	v_fma_f32 v112, v144, v112, v160
	v_mul_f32_e32 v113, v113, v209
	v_mul_f32_e32 v113, v1, v113
	v_fma_f32 v113, v145, v113, v161
	v_mul_f32_e32 v114, v114, v209
	v_mul_f32_e32 v114, v2, v114
	v_fma_f32 v114, v146, v114, v162
	v_mul_f32_e32 v115, v115, v209
	v_mul_f32_e32 v115, v3, v115
	v_fma_f32 v115, v147, v115, v163
	v_cvt_pk_bf16_f32 v180, v112, v113
	v_cvt_pk_bf16_f32 v181, v114, v115
	global_store_dwordx2 v196, v[180:181], s[10:11]
	s_nop 0
	v_mul_f32_e32 v116, v116, v209
	v_mul_f32_e32 v116, v4, v116
	v_fma_f32 v116, v148, v116, v164
	v_mul_f32_e32 v117, v117, v209
	v_mul_f32_e32 v117, v5, v117
	v_fma_f32 v117, v149, v117, v165
	v_mul_f32_e32 v118, v118, v209
	v_mul_f32_e32 v118, v6, v118
	v_fma_f32 v118, v150, v118, v166
	v_mul_f32_e32 v119, v119, v209
	v_mul_f32_e32 v119, v7, v119
	v_fma_f32 v119, v151, v119, v167
	v_cvt_pk_bf16_f32 v180, v116, v117
	v_cvt_pk_bf16_f32 v181, v118, v119
	global_store_dwordx2 v196, v[180:181], s[10:11] offset:512
	s_nop 0
	v_mul_f32_e32 v120, v120, v209
	v_mul_f32_e32 v120, v8, v120
	v_fma_f32 v120, v152, v120, v168
	v_mul_f32_e32 v121, v121, v209
	v_mul_f32_e32 v121, v9, v121
	v_fma_f32 v121, v153, v121, v169
	v_mul_f32_e32 v122, v122, v209
	v_mul_f32_e32 v122, v10, v122
	v_fma_f32 v122, v154, v122, v170
	v_mul_f32_e32 v123, v123, v209
	v_mul_f32_e32 v123, v11, v123
	v_fma_f32 v123, v155, v123, v171
	v_cvt_pk_bf16_f32 v180, v120, v121
	v_cvt_pk_bf16_f32 v181, v122, v123
	global_store_dwordx2 v196, v[180:181], s[10:11] offset:1024
	s_nop 0
	v_mul_f32_e32 v124, v124, v209
	v_mul_f32_e32 v124, v12, v124
	v_fma_f32 v124, v156, v124, v172
	v_mul_f32_e32 v125, v125, v209
	v_mul_f32_e32 v125, v13, v125
	v_fma_f32 v125, v157, v125, v173
	v_mul_f32_e32 v126, v126, v209
	v_mul_f32_e32 v126, v14, v126
	v_fma_f32 v126, v158, v126, v174
	v_mul_f32_e32 v127, v127, v209
	v_mul_f32_e32 v127, v15, v127
	v_fma_f32 v127, v159, v127, v175
	v_cvt_pk_bf16_f32 v180, v124, v125
	v_cvt_pk_bf16_f32 v181, v126, v127
	global_store_dwordx2 v196, v[180:181], s[10:11] offset:1536
	s_nop 0
	v_mul_f32_e32 v128, v128, v210
	v_mul_f32_e32 v128, v0, v128
	v_fma_f32 v128, v144, v128, v160
	v_mul_f32_e32 v129, v129, v210
	v_mul_f32_e32 v129, v1, v129
	v_fma_f32 v129, v145, v129, v161
	v_mul_f32_e32 v130, v130, v210
	v_mul_f32_e32 v130, v2, v130
	v_fma_f32 v130, v146, v130, v162
	v_mul_f32_e32 v131, v131, v210
	v_mul_f32_e32 v131, v3, v131
	v_fma_f32 v131, v147, v131, v163
	v_cvt_pk_bf16_f32 v180, v128, v129
	v_cvt_pk_bf16_f32 v181, v130, v131
	global_store_dwordx2 v196, v[180:181], s[10:11] offset:2048
	s_nop 0
	v_mul_f32_e32 v132, v132, v210
	v_mul_f32_e32 v132, v4, v132
	v_fma_f32 v132, v148, v132, v164
	v_mul_f32_e32 v133, v133, v210
	v_mul_f32_e32 v133, v5, v133
	v_fma_f32 v133, v149, v133, v165
	v_mul_f32_e32 v134, v134, v210
	v_mul_f32_e32 v134, v6, v134
	v_fma_f32 v134, v150, v134, v166
	v_mul_f32_e32 v135, v135, v210
	v_mul_f32_e32 v135, v7, v135
	v_fma_f32 v135, v151, v135, v167
	v_cvt_pk_bf16_f32 v180, v132, v133
	v_cvt_pk_bf16_f32 v181, v134, v135
	global_store_dwordx2 v196, v[180:181], s[10:11] offset:2560
	s_nop 0
	v_mul_f32_e32 v136, v136, v210
	v_mul_f32_e32 v136, v8, v136
	v_fma_f32 v136, v152, v136, v168
	v_mul_f32_e32 v137, v137, v210
	v_mul_f32_e32 v137, v9, v137
	v_fma_f32 v137, v153, v137, v169
	v_mul_f32_e32 v138, v138, v210
	v_mul_f32_e32 v138, v10, v138
	v_fma_f32 v138, v154, v138, v170
	v_mul_f32_e32 v139, v139, v210
	v_mul_f32_e32 v139, v11, v139
	v_fma_f32 v139, v155, v139, v171
	v_cvt_pk_bf16_f32 v180, v136, v137
	v_cvt_pk_bf16_f32 v181, v138, v139
	global_store_dwordx2 v196, v[180:181], s[10:11] offset:3072
	s_nop 0
	v_mul_f32_e32 v140, v140, v210
	v_mul_f32_e32 v140, v12, v140
	v_fma_f32 v140, v156, v140, v172
	v_mul_f32_e32 v141, v141, v210
	v_mul_f32_e32 v141, v13, v141
	v_fma_f32 v141, v157, v141, v173
	v_mul_f32_e32 v142, v142, v210
	v_mul_f32_e32 v142, v14, v142
	v_fma_f32 v142, v158, v142, v174
	v_mul_f32_e32 v143, v143, v210
	v_mul_f32_e32 v143, v15, v143
	v_fma_f32 v143, v159, v143, v175
	v_cvt_pk_bf16_f32 v180, v140, v141
	v_cvt_pk_bf16_f32 v181, v142, v143
	global_store_dwordx2 v196, v[180:181], s[10:11] offset:3584
	s_nop 0
	s_add_u32 s14, s14, 0x2000
	s_addc_u32 s15, s15, 0
	global_load_dwordx4 v[112:115], v194, s[14:15]
	global_load_dwordx4 v[116:119], v194, s[14:15] offset:1024
	global_load_dwordx4 v[120:123], v194, s[14:15] offset:2048
	global_load_dwordx4 v[124:127], v194, s[14:15] offset:3072
	global_load_dwordx4 v[128:131], v195, s[14:15]
	global_load_dwordx4 v[132:135], v195, s[14:15] offset:1024
	global_load_dwordx4 v[136:139], v195, s[14:15] offset:2048
	global_load_dwordx4 v[140:143], v195, s[14:15] offset:3072
	s_waitcnt vmcnt(48)
	v_pk_mul_f32 v[178:179], v[16:17], v[16:17]
	v_pk_fma_f32 v[178:179], v[18:19], v[18:19], v[178:179]
	v_pk_fma_f32 v[178:179], v[20:21], v[20:21], v[178:179]
	v_pk_fma_f32 v[178:179], v[22:23], v[22:23], v[178:179]
	v_pk_fma_f32 v[178:179], v[24:25], v[24:25], v[178:179]
	v_pk_fma_f32 v[178:179], v[26:27], v[26:27], v[178:179]
	v_pk_fma_f32 v[178:179], v[28:29], v[28:29], v[178:179]
	v_pk_fma_f32 v[178:179], v[30:31], v[30:31], v[178:179]
	v_pk_mul_f32 v[180:181], v[32:33], v[32:33]
	v_pk_fma_f32 v[180:181], v[34:35], v[34:35], v[180:181]
	v_pk_fma_f32 v[180:181], v[36:37], v[36:37], v[180:181]
	v_pk_fma_f32 v[180:181], v[38:39], v[38:39], v[180:181]
	v_pk_fma_f32 v[180:181], v[40:41], v[40:41], v[180:181]
	v_pk_fma_f32 v[180:181], v[42:43], v[42:43], v[180:181]
	v_pk_fma_f32 v[180:181], v[44:45], v[44:45], v[180:181]
	v_pk_fma_f32 v[180:181], v[46:47], v[46:47], v[180:181]
	v_add_f32_e32 v176, v178, v179
	v_add_f32_e32 v177, v180, v181
	ds_bpermute_b32 v178, v198, v176
	ds_bpermute_b32 v179, v198, v177
	s_waitcnt lgkmcnt(0)
	v_add_f32_e32 v176, v176, v178
	v_add_f32_e32 v177, v177, v179
	ds_bpermute_b32 v178, v199, v176
	ds_bpermute_b32 v179, v199, v177
	s_waitcnt lgkmcnt(0)
	v_add_f32_e32 v176, v176, v178
	v_add_f32_e32 v177, v177, v179
	ds_bpermute_b32 v178, v200, v176
	ds_bpermute_b32 v179, v200, v177
	s_waitcnt lgkmcnt(0)
	v_add_f32_e32 v176, v176, v178
	v_add_f32_e32 v177, v177, v179
	ds_bpermute_b32 v178, v201, v176
	ds_bpermute_b32 v179, v201, v177
	s_waitcnt lgkmcnt(0)
	v_add_f32_e32 v176, v176, v178
	v_add_f32_e32 v177, v177, v179
	ds_bpermute_b32 v178, v202, v176
	ds_bpermute_b32 v179, v202, v177
	s_waitcnt lgkmcnt(0)
	v_add_f32_e32 v176, v176, v178
	v_add_f32_e32 v177, v177, v179
	ds_bpermute_b32 v178, v203, v176
	ds_bpermute_b32 v179, v203, v177
	s_waitcnt lgkmcnt(0)
	v_add_f32_e32 v176, v176, v178
	v_add_f32_e32 v177, v177, v179
	v_fmamk_f32 v176, v176, 0x3a800000, v208
	v_mul_f32_e32 v178, 0x4b800000, v176
	v_cmp_gt_f32_e32 vcc, s27, v176
	s_nop 1
	v_cndmask_b32_e32 v176, v176, v178, vcc
	v_rsq_f32_e32 v209, v176
	s_nop 0
	v_mul_f32_e32 v178, 0x45800000, v209
	v_cndmask_b32_e32 v209, v209, v178, vcc
	v_fmamk_f32 v177, v177, 0x3a800000, v208
	v_mul_f32_e32 v178, 0x4b800000, v177
	v_cmp_gt_f32_e32 vcc, s27, v177
	s_nop 1
	v_cndmask_b32_e32 v177, v177, v178, vcc
	v_rsq_f32_e32 v210, v177
	s_nop 0
	v_mul_f32_e32 v178, 0x45800000, v210
	v_cndmask_b32_e32 v210, v210, v178, vcc
	s_add_u32 s10, s10, 0x1000
	s_addc_u32 s11, s11, 0
	v_mul_f32_e32 v16, v16, v209
	v_mul_f32_e32 v16, v0, v16
	v_fma_f32 v16, v144, v16, v160
	v_mul_f32_e32 v17, v17, v209
	v_mul_f32_e32 v17, v1, v17
	v_fma_f32 v17, v145, v17, v161
	v_mul_f32_e32 v18, v18, v209
	v_mul_f32_e32 v18, v2, v18
	v_fma_f32 v18, v146, v18, v162
	v_mul_f32_e32 v19, v19, v209
	v_mul_f32_e32 v19, v3, v19
	v_fma_f32 v19, v147, v19, v163
	v_cvt_pk_bf16_f32 v180, v16, v17
	v_cvt_pk_bf16_f32 v181, v18, v19
	global_store_dwordx2 v196, v[180:181], s[10:11]
	s_nop 0
	v_mul_f32_e32 v20, v20, v209
	v_mul_f32_e32 v20, v4, v20
	v_fma_f32 v20, v148, v20, v164
	v_mul_f32_e32 v21, v21, v209
	v_mul_f32_e32 v21, v5, v21
	v_fma_f32 v21, v149, v21, v165
	v_mul_f32_e32 v22, v22, v209
	v_mul_f32_e32 v22, v6, v22
	v_fma_f32 v22, v150, v22, v166
	v_mul_f32_e32 v23, v23, v209
	v_mul_f32_e32 v23, v7, v23
	v_fma_f32 v23, v151, v23, v167
	v_cvt_pk_bf16_f32 v180, v20, v21
	v_cvt_pk_bf16_f32 v181, v22, v23
	global_store_dwordx2 v196, v[180:181], s[10:11] offset:512
	s_nop 0
	v_mul_f32_e32 v24, v24, v209
	v_mul_f32_e32 v24, v8, v24
	v_fma_f32 v24, v152, v24, v168
	v_mul_f32_e32 v25, v25, v209
	v_mul_f32_e32 v25, v9, v25
	v_fma_f32 v25, v153, v25, v169
	v_mul_f32_e32 v26, v26, v209
	v_mul_f32_e32 v26, v10, v26
	v_fma_f32 v26, v154, v26, v170
	v_mul_f32_e32 v27, v27, v209
	v_mul_f32_e32 v27, v11, v27
	v_fma_f32 v27, v155, v27, v171
	v_cvt_pk_bf16_f32 v180, v24, v25
	v_cvt_pk_bf16_f32 v181, v26, v27
	global_store_dwordx2 v196, v[180:181], s[10:11] offset:1024
	s_nop 0
	v_mul_f32_e32 v28, v28, v209
	v_mul_f32_e32 v28, v12, v28
	v_fma_f32 v28, v156, v28, v172
	v_mul_f32_e32 v29, v29, v209
	v_mul_f32_e32 v29, v13, v29
	v_fma_f32 v29, v157, v29, v173
	v_mul_f32_e32 v30, v30, v209
	v_mul_f32_e32 v30, v14, v30
	v_fma_f32 v30, v158, v30, v174
	v_mul_f32_e32 v31, v31, v209
	v_mul_f32_e32 v31, v15, v31
	v_fma_f32 v31, v159, v31, v175
	v_cvt_pk_bf16_f32 v180, v28, v29
	v_cvt_pk_bf16_f32 v181, v30, v31
	global_store_dwordx2 v196, v[180:181], s[10:11] offset:1536
	s_nop 0
	v_mul_f32_e32 v32, v32, v210
	v_mul_f32_e32 v32, v0, v32
	v_fma_f32 v32, v144, v32, v160
	v_mul_f32_e32 v33, v33, v210
	v_mul_f32_e32 v33, v1, v33
	v_fma_f32 v33, v145, v33, v161
	v_mul_f32_e32 v34, v34, v210
	v_mul_f32_e32 v34, v2, v34
	v_fma_f32 v34, v146, v34, v162
	v_mul_f32_e32 v35, v35, v210
	v_mul_f32_e32 v35, v3, v35
	v_fma_f32 v35, v147, v35, v163
	v_cvt_pk_bf16_f32 v180, v32, v33
	v_cvt_pk_bf16_f32 v181, v34, v35
	global_store_dwordx2 v196, v[180:181], s[10:11] offset:2048
	s_nop 0
	v_mul_f32_e32 v36, v36, v210
	v_mul_f32_e32 v36, v4, v36
	v_fma_f32 v36, v148, v36, v164
	v_mul_f32_e32 v37, v37, v210
	v_mul_f32_e32 v37, v5, v37
	v_fma_f32 v37, v149, v37, v165
	v_mul_f32_e32 v38, v38, v210
	v_mul_f32_e32 v38, v6, v38
	v_fma_f32 v38, v150, v38, v166
	v_mul_f32_e32 v39, v39, v210
	v_mul_f32_e32 v39, v7, v39
	v_fma_f32 v39, v151, v39, v167
	v_cvt_pk_bf16_f32 v180, v36, v37
	v_cvt_pk_bf16_f32 v181, v38, v39
	global_store_dwordx2 v196, v[180:181], s[10:11] offset:2560
	s_nop 0
	v_mul_f32_e32 v40, v40, v210
	v_mul_f32_e32 v40, v8, v40
	v_fma_f32 v40, v152, v40, v168
	v_mul_f32_e32 v41, v41, v210
	v_mul_f32_e32 v41, v9, v41
	v_fma_f32 v41, v153, v41, v169
	v_mul_f32_e32 v42, v42, v210
	v_mul_f32_e32 v42, v10, v42
	v_fma_f32 v42, v154, v42, v170
	v_mul_f32_e32 v43, v43, v210
	v_mul_f32_e32 v43, v11, v43
	v_fma_f32 v43, v155, v43, v171
	v_cvt_pk_bf16_f32 v180, v40, v41
	v_cvt_pk_bf16_f32 v181, v42, v43
	global_store_dwordx2 v196, v[180:181], s[10:11] offset:3072
	s_nop 0
	v_mul_f32_e32 v44, v44, v210
	v_mul_f32_e32 v44, v12, v44
	v_fma_f32 v44, v156, v44, v172
	v_mul_f32_e32 v45, v45, v210
	v_mul_f32_e32 v45, v13, v45
	v_fma_f32 v45, v157, v45, v173
	v_mul_f32_e32 v46, v46, v210
	v_mul_f32_e32 v46, v14, v46
	v_fma_f32 v46, v158, v46, v174
	v_mul_f32_e32 v47, v47, v210
	v_mul_f32_e32 v47, v15, v47
	v_fma_f32 v47, v159, v47, v175
	v_cvt_pk_bf16_f32 v180, v44, v45
	v_cvt_pk_bf16_f32 v181, v46, v47
	global_store_dwordx2 v196, v[180:181], s[10:11] offset:3584
	s_nop 0
	s_add_u32 s14, s14, 0x2000
	s_addc_u32 s15, s15, 0
	global_load_dwordx4 v[16:19], v194, s[14:15]
	global_load_dwordx4 v[20:23], v194, s[14:15] offset:1024
	global_load_dwordx4 v[24:27], v194, s[14:15] offset:2048
	global_load_dwordx4 v[28:31], v194, s[14:15] offset:3072
	global_load_dwordx4 v[32:35], v195, s[14:15]
	global_load_dwordx4 v[36:39], v195, s[14:15] offset:1024
	global_load_dwordx4 v[40:43], v195, s[14:15] offset:2048
	global_load_dwordx4 v[44:47], v195, s[14:15] offset:3072
	s_waitcnt vmcnt(48)
	v_pk_mul_f32 v[178:179], v[48:49], v[48:49]
	v_pk_fma_f32 v[178:179], v[50:51], v[50:51], v[178:179]
	v_pk_fma_f32 v[178:179], v[52:53], v[52:53], v[178:179]
	v_pk_fma_f32 v[178:179], v[54:55], v[54:55], v[178:179]
	v_pk_fma_f32 v[178:179], v[56:57], v[56:57], v[178:179]
	v_pk_fma_f32 v[178:179], v[58:59], v[58:59], v[178:179]
	v_pk_fma_f32 v[178:179], v[60:61], v[60:61], v[178:179]
	v_pk_fma_f32 v[178:179], v[62:63], v[62:63], v[178:179]
	v_pk_mul_f32 v[180:181], v[64:65], v[64:65]
	v_pk_fma_f32 v[180:181], v[66:67], v[66:67], v[180:181]
	v_pk_fma_f32 v[180:181], v[68:69], v[68:69], v[180:181]
	v_pk_fma_f32 v[180:181], v[70:71], v[70:71], v[180:181]
	v_pk_fma_f32 v[180:181], v[72:73], v[72:73], v[180:181]
	v_pk_fma_f32 v[180:181], v[74:75], v[74:75], v[180:181]
	v_pk_fma_f32 v[180:181], v[76:77], v[76:77], v[180:181]
	v_pk_fma_f32 v[180:181], v[78:79], v[78:79], v[180:181]
	v_add_f32_e32 v176, v178, v179
	v_add_f32_e32 v177, v180, v181
	ds_bpermute_b32 v178, v198, v176
	ds_bpermute_b32 v179, v198, v177
	s_waitcnt lgkmcnt(0)
	v_add_f32_e32 v176, v176, v178
	v_add_f32_e32 v177, v177, v179
	ds_bpermute_b32 v178, v199, v176
	ds_bpermute_b32 v179, v199, v177
	s_waitcnt lgkmcnt(0)
	v_add_f32_e32 v176, v176, v178
	v_add_f32_e32 v177, v177, v179
	ds_bpermute_b32 v178, v200, v176
	ds_bpermute_b32 v179, v200, v177
	s_waitcnt lgkmcnt(0)
	v_add_f32_e32 v176, v176, v178
	v_add_f32_e32 v177, v177, v179
	ds_bpermute_b32 v178, v201, v176
	ds_bpermute_b32 v179, v201, v177
	s_waitcnt lgkmcnt(0)
	v_add_f32_e32 v176, v176, v178
	v_add_f32_e32 v177, v177, v179
	ds_bpermute_b32 v178, v202, v176
	ds_bpermute_b32 v179, v202, v177
	s_waitcnt lgkmcnt(0)
	v_add_f32_e32 v176, v176, v178
	v_add_f32_e32 v177, v177, v179
	ds_bpermute_b32 v178, v203, v176
	ds_bpermute_b32 v179, v203, v177
	s_waitcnt lgkmcnt(0)
	v_add_f32_e32 v176, v176, v178
	v_add_f32_e32 v177, v177, v179
	v_fmamk_f32 v176, v176, 0x3a800000, v208
	v_mul_f32_e32 v178, 0x4b800000, v176
	v_cmp_gt_f32_e32 vcc, s27, v176
	s_nop 1
	v_cndmask_b32_e32 v176, v176, v178, vcc
	v_rsq_f32_e32 v209, v176
	s_nop 0
	v_mul_f32_e32 v178, 0x45800000, v209
	v_cndmask_b32_e32 v209, v209, v178, vcc
	v_fmamk_f32 v177, v177, 0x3a800000, v208
	v_mul_f32_e32 v178, 0x4b800000, v177
	v_cmp_gt_f32_e32 vcc, s27, v177
	s_nop 1
	v_cndmask_b32_e32 v177, v177, v178, vcc
	v_rsq_f32_e32 v210, v177
	s_nop 0
	v_mul_f32_e32 v178, 0x45800000, v210
	v_cndmask_b32_e32 v210, v210, v178, vcc
	s_add_u32 s10, s10, 0x1000
	s_addc_u32 s11, s11, 0
	v_mul_f32_e32 v48, v48, v209
	v_mul_f32_e32 v48, v0, v48
	v_fma_f32 v48, v144, v48, v160
	v_mul_f32_e32 v49, v49, v209
	v_mul_f32_e32 v49, v1, v49
	v_fma_f32 v49, v145, v49, v161
	v_mul_f32_e32 v50, v50, v209
	v_mul_f32_e32 v50, v2, v50
	v_fma_f32 v50, v146, v50, v162
	v_mul_f32_e32 v51, v51, v209
	v_mul_f32_e32 v51, v3, v51
	v_fma_f32 v51, v147, v51, v163
	v_cvt_pk_bf16_f32 v180, v48, v49
	v_cvt_pk_bf16_f32 v181, v50, v51
	global_store_dwordx2 v196, v[180:181], s[10:11]
	s_nop 0
	v_mul_f32_e32 v52, v52, v209
	v_mul_f32_e32 v52, v4, v52
	v_fma_f32 v52, v148, v52, v164
	v_mul_f32_e32 v53, v53, v209
	v_mul_f32_e32 v53, v5, v53
	v_fma_f32 v53, v149, v53, v165
	v_mul_f32_e32 v54, v54, v209
	v_mul_f32_e32 v54, v6, v54
	v_fma_f32 v54, v150, v54, v166
	v_mul_f32_e32 v55, v55, v209
	v_mul_f32_e32 v55, v7, v55
	v_fma_f32 v55, v151, v55, v167
	v_cvt_pk_bf16_f32 v180, v52, v53
	v_cvt_pk_bf16_f32 v181, v54, v55
	global_store_dwordx2 v196, v[180:181], s[10:11] offset:512
	s_nop 0
	v_mul_f32_e32 v56, v56, v209
	v_mul_f32_e32 v56, v8, v56
	v_fma_f32 v56, v152, v56, v168
	v_mul_f32_e32 v57, v57, v209
	v_mul_f32_e32 v57, v9, v57
	v_fma_f32 v57, v153, v57, v169
	v_mul_f32_e32 v58, v58, v209
	v_mul_f32_e32 v58, v10, v58
	v_fma_f32 v58, v154, v58, v170
	v_mul_f32_e32 v59, v59, v209
	v_mul_f32_e32 v59, v11, v59
	v_fma_f32 v59, v155, v59, v171
	v_cvt_pk_bf16_f32 v180, v56, v57
	v_cvt_pk_bf16_f32 v181, v58, v59
	global_store_dwordx2 v196, v[180:181], s[10:11] offset:1024
	s_nop 0
	v_mul_f32_e32 v60, v60, v209
	v_mul_f32_e32 v60, v12, v60
	v_fma_f32 v60, v156, v60, v172
	v_mul_f32_e32 v61, v61, v209
	v_mul_f32_e32 v61, v13, v61
	v_fma_f32 v61, v157, v61, v173
	v_mul_f32_e32 v62, v62, v209
	v_mul_f32_e32 v62, v14, v62
	v_fma_f32 v62, v158, v62, v174
	v_mul_f32_e32 v63, v63, v209
	v_mul_f32_e32 v63, v15, v63
	v_fma_f32 v63, v159, v63, v175
	v_cvt_pk_bf16_f32 v180, v60, v61
	v_cvt_pk_bf16_f32 v181, v62, v63
	global_store_dwordx2 v196, v[180:181], s[10:11] offset:1536
	s_nop 0
	v_mul_f32_e32 v64, v64, v210
	v_mul_f32_e32 v64, v0, v64
	v_fma_f32 v64, v144, v64, v160
	v_mul_f32_e32 v65, v65, v210
	v_mul_f32_e32 v65, v1, v65
	v_fma_f32 v65, v145, v65, v161
	v_mul_f32_e32 v66, v66, v210
	v_mul_f32_e32 v66, v2, v66
	v_fma_f32 v66, v146, v66, v162
	v_mul_f32_e32 v67, v67, v210
	v_mul_f32_e32 v67, v3, v67
	v_fma_f32 v67, v147, v67, v163
	v_cvt_pk_bf16_f32 v180, v64, v65
	v_cvt_pk_bf16_f32 v181, v66, v67
	global_store_dwordx2 v196, v[180:181], s[10:11] offset:2048
	s_nop 0
	v_mul_f32_e32 v68, v68, v210
	v_mul_f32_e32 v68, v4, v68
	v_fma_f32 v68, v148, v68, v164
	v_mul_f32_e32 v69, v69, v210
	v_mul_f32_e32 v69, v5, v69
	v_fma_f32 v69, v149, v69, v165
	v_mul_f32_e32 v70, v70, v210
	v_mul_f32_e32 v70, v6, v70
	v_fma_f32 v70, v150, v70, v166
	v_mul_f32_e32 v71, v71, v210
	v_mul_f32_e32 v71, v7, v71
	v_fma_f32 v71, v151, v71, v167
	v_cvt_pk_bf16_f32 v180, v68, v69
	v_cvt_pk_bf16_f32 v181, v70, v71
	global_store_dwordx2 v196, v[180:181], s[10:11] offset:2560
	s_nop 0
	v_mul_f32_e32 v72, v72, v210
	v_mul_f32_e32 v72, v8, v72
	v_fma_f32 v72, v152, v72, v168
	v_mul_f32_e32 v73, v73, v210
	v_mul_f32_e32 v73, v9, v73
	v_fma_f32 v73, v153, v73, v169
	v_mul_f32_e32 v74, v74, v210
	v_mul_f32_e32 v74, v10, v74
	v_fma_f32 v74, v154, v74, v170
	v_mul_f32_e32 v75, v75, v210
	v_mul_f32_e32 v75, v11, v75
	v_fma_f32 v75, v155, v75, v171
	v_cvt_pk_bf16_f32 v180, v72, v73
	v_cvt_pk_bf16_f32 v181, v74, v75
	global_store_dwordx2 v196, v[180:181], s[10:11] offset:3072
	s_nop 0
	v_mul_f32_e32 v76, v76, v210
	v_mul_f32_e32 v76, v12, v76
	v_fma_f32 v76, v156, v76, v172
	v_mul_f32_e32 v77, v77, v210
	v_mul_f32_e32 v77, v13, v77
	v_fma_f32 v77, v157, v77, v173
	v_mul_f32_e32 v78, v78, v210
	v_mul_f32_e32 v78, v14, v78
	v_fma_f32 v78, v158, v78, v174
	v_mul_f32_e32 v79, v79, v210
	v_mul_f32_e32 v79, v15, v79
	v_fma_f32 v79, v159, v79, v175
	v_cvt_pk_bf16_f32 v180, v76, v77
	v_cvt_pk_bf16_f32 v181, v78, v79
	global_store_dwordx2 v196, v[180:181], s[10:11] offset:3584
	s_nop 0
	s_add_u32 s14, s14, 0x2000
	s_addc_u32 s15, s15, 0
	global_load_dwordx4 v[48:51], v194, s[14:15]
	global_load_dwordx4 v[52:55], v194, s[14:15] offset:1024
	global_load_dwordx4 v[56:59], v194, s[14:15] offset:2048
	global_load_dwordx4 v[60:63], v194, s[14:15] offset:3072
	global_load_dwordx4 v[64:67], v195, s[14:15]
	global_load_dwordx4 v[68:71], v195, s[14:15] offset:1024
	global_load_dwordx4 v[72:75], v195, s[14:15] offset:2048
	global_load_dwordx4 v[76:79], v195, s[14:15] offset:3072
	s_waitcnt vmcnt(48)
	v_pk_mul_f32 v[178:179], v[80:81], v[80:81]
	v_pk_fma_f32 v[178:179], v[82:83], v[82:83], v[178:179]
	v_pk_fma_f32 v[178:179], v[84:85], v[84:85], v[178:179]
	v_pk_fma_f32 v[178:179], v[86:87], v[86:87], v[178:179]
	v_pk_fma_f32 v[178:179], v[88:89], v[88:89], v[178:179]
	v_pk_fma_f32 v[178:179], v[90:91], v[90:91], v[178:179]
	v_pk_fma_f32 v[178:179], v[92:93], v[92:93], v[178:179]
	v_pk_fma_f32 v[178:179], v[94:95], v[94:95], v[178:179]
	v_pk_mul_f32 v[180:181], v[96:97], v[96:97]
	v_pk_fma_f32 v[180:181], v[98:99], v[98:99], v[180:181]
	v_pk_fma_f32 v[180:181], v[100:101], v[100:101], v[180:181]
	v_pk_fma_f32 v[180:181], v[102:103], v[102:103], v[180:181]
	v_pk_fma_f32 v[180:181], v[104:105], v[104:105], v[180:181]
	v_pk_fma_f32 v[180:181], v[106:107], v[106:107], v[180:181]
	v_pk_fma_f32 v[180:181], v[108:109], v[108:109], v[180:181]
	v_pk_fma_f32 v[180:181], v[110:111], v[110:111], v[180:181]
	v_add_f32_e32 v176, v178, v179
	v_add_f32_e32 v177, v180, v181
	ds_bpermute_b32 v178, v198, v176
	ds_bpermute_b32 v179, v198, v177
	s_waitcnt lgkmcnt(0)
	v_add_f32_e32 v176, v176, v178
	v_add_f32_e32 v177, v177, v179
	ds_bpermute_b32 v178, v199, v176
	ds_bpermute_b32 v179, v199, v177
	s_waitcnt lgkmcnt(0)
	v_add_f32_e32 v176, v176, v178
	v_add_f32_e32 v177, v177, v179
	ds_bpermute_b32 v178, v200, v176
	ds_bpermute_b32 v179, v200, v177
	s_waitcnt lgkmcnt(0)
	v_add_f32_e32 v176, v176, v178
	v_add_f32_e32 v177, v177, v179
	ds_bpermute_b32 v178, v201, v176
	ds_bpermute_b32 v179, v201, v177
	s_waitcnt lgkmcnt(0)
	v_add_f32_e32 v176, v176, v178
	v_add_f32_e32 v177, v177, v179
	ds_bpermute_b32 v178, v202, v176
	ds_bpermute_b32 v179, v202, v177
	s_waitcnt lgkmcnt(0)
	v_add_f32_e32 v176, v176, v178
	v_add_f32_e32 v177, v177, v179
	ds_bpermute_b32 v178, v203, v176
	ds_bpermute_b32 v179, v203, v177
	s_waitcnt lgkmcnt(0)
	v_add_f32_e32 v176, v176, v178
	v_add_f32_e32 v177, v177, v179
	v_fmamk_f32 v176, v176, 0x3a800000, v208
	v_mul_f32_e32 v178, 0x4b800000, v176
	v_cmp_gt_f32_e32 vcc, s27, v176
	s_nop 1
	v_cndmask_b32_e32 v176, v176, v178, vcc
	v_rsq_f32_e32 v209, v176
	s_nop 0
	v_mul_f32_e32 v178, 0x45800000, v209
	v_cndmask_b32_e32 v209, v209, v178, vcc
	v_fmamk_f32 v177, v177, 0x3a800000, v208
	v_mul_f32_e32 v178, 0x4b800000, v177
	v_cmp_gt_f32_e32 vcc, s27, v177
	s_nop 1
	v_cndmask_b32_e32 v177, v177, v178, vcc
	v_rsq_f32_e32 v210, v177
	s_nop 0
	v_mul_f32_e32 v178, 0x45800000, v210
	v_cndmask_b32_e32 v210, v210, v178, vcc
	s_add_u32 s10, s10, 0x1000
	s_addc_u32 s11, s11, 0
	v_mul_f32_e32 v80, v80, v209
	v_mul_f32_e32 v80, v0, v80
	v_fma_f32 v80, v144, v80, v160
	v_mul_f32_e32 v81, v81, v209
	v_mul_f32_e32 v81, v1, v81
	v_fma_f32 v81, v145, v81, v161
	v_mul_f32_e32 v82, v82, v209
	v_mul_f32_e32 v82, v2, v82
	v_fma_f32 v82, v146, v82, v162
	v_mul_f32_e32 v83, v83, v209
	v_mul_f32_e32 v83, v3, v83
	v_fma_f32 v83, v147, v83, v163
	v_cvt_pk_bf16_f32 v180, v80, v81
	v_cvt_pk_bf16_f32 v181, v82, v83
	global_store_dwordx2 v196, v[180:181], s[10:11]
	s_nop 0
	v_mul_f32_e32 v84, v84, v209
	v_mul_f32_e32 v84, v4, v84
	v_fma_f32 v84, v148, v84, v164
	v_mul_f32_e32 v85, v85, v209
	v_mul_f32_e32 v85, v5, v85
	v_fma_f32 v85, v149, v85, v165
	v_mul_f32_e32 v86, v86, v209
	v_mul_f32_e32 v86, v6, v86
	v_fma_f32 v86, v150, v86, v166
	v_mul_f32_e32 v87, v87, v209
	v_mul_f32_e32 v87, v7, v87
	v_fma_f32 v87, v151, v87, v167
	v_cvt_pk_bf16_f32 v180, v84, v85
	v_cvt_pk_bf16_f32 v181, v86, v87
	global_store_dwordx2 v196, v[180:181], s[10:11] offset:512
	s_nop 0
	v_mul_f32_e32 v88, v88, v209
	v_mul_f32_e32 v88, v8, v88
	v_fma_f32 v88, v152, v88, v168
	v_mul_f32_e32 v89, v89, v209
	v_mul_f32_e32 v89, v9, v89
	v_fma_f32 v89, v153, v89, v169
	v_mul_f32_e32 v90, v90, v209
	v_mul_f32_e32 v90, v10, v90
	v_fma_f32 v90, v154, v90, v170
	v_mul_f32_e32 v91, v91, v209
	v_mul_f32_e32 v91, v11, v91
	v_fma_f32 v91, v155, v91, v171
	v_cvt_pk_bf16_f32 v180, v88, v89
	v_cvt_pk_bf16_f32 v181, v90, v91
	global_store_dwordx2 v196, v[180:181], s[10:11] offset:1024
	s_nop 0
	v_mul_f32_e32 v92, v92, v209
	v_mul_f32_e32 v92, v12, v92
	v_fma_f32 v92, v156, v92, v172
	v_mul_f32_e32 v93, v93, v209
	v_mul_f32_e32 v93, v13, v93
	v_fma_f32 v93, v157, v93, v173
	v_mul_f32_e32 v94, v94, v209
	v_mul_f32_e32 v94, v14, v94
	v_fma_f32 v94, v158, v94, v174
	v_mul_f32_e32 v95, v95, v209
	v_mul_f32_e32 v95, v15, v95
	v_fma_f32 v95, v159, v95, v175
	v_cvt_pk_bf16_f32 v180, v92, v93
	v_cvt_pk_bf16_f32 v181, v94, v95
	global_store_dwordx2 v196, v[180:181], s[10:11] offset:1536
	s_nop 0
	v_mul_f32_e32 v96, v96, v210
	v_mul_f32_e32 v96, v0, v96
	v_fma_f32 v96, v144, v96, v160
	v_mul_f32_e32 v97, v97, v210
	v_mul_f32_e32 v97, v1, v97
	v_fma_f32 v97, v145, v97, v161
	v_mul_f32_e32 v98, v98, v210
	v_mul_f32_e32 v98, v2, v98
	v_fma_f32 v98, v146, v98, v162
	v_mul_f32_e32 v99, v99, v210
	v_mul_f32_e32 v99, v3, v99
	v_fma_f32 v99, v147, v99, v163
	v_cvt_pk_bf16_f32 v180, v96, v97
	v_cvt_pk_bf16_f32 v181, v98, v99
	global_store_dwordx2 v196, v[180:181], s[10:11] offset:2048
	s_nop 0
	v_mul_f32_e32 v100, v100, v210
	v_mul_f32_e32 v100, v4, v100
	v_fma_f32 v100, v148, v100, v164
	v_mul_f32_e32 v101, v101, v210
	v_mul_f32_e32 v101, v5, v101
	v_fma_f32 v101, v149, v101, v165
	v_mul_f32_e32 v102, v102, v210
	v_mul_f32_e32 v102, v6, v102
	v_fma_f32 v102, v150, v102, v166
	v_mul_f32_e32 v103, v103, v210
	v_mul_f32_e32 v103, v7, v103
	v_fma_f32 v103, v151, v103, v167
	v_cvt_pk_bf16_f32 v180, v100, v101
	v_cvt_pk_bf16_f32 v181, v102, v103
	global_store_dwordx2 v196, v[180:181], s[10:11] offset:2560
	s_nop 0
	v_mul_f32_e32 v104, v104, v210
	v_mul_f32_e32 v104, v8, v104
	v_fma_f32 v104, v152, v104, v168
	v_mul_f32_e32 v105, v105, v210
	v_mul_f32_e32 v105, v9, v105
	v_fma_f32 v105, v153, v105, v169
	v_mul_f32_e32 v106, v106, v210
	v_mul_f32_e32 v106, v10, v106
	v_fma_f32 v106, v154, v106, v170
	v_mul_f32_e32 v107, v107, v210
	v_mul_f32_e32 v107, v11, v107
	v_fma_f32 v107, v155, v107, v171
	v_cvt_pk_bf16_f32 v180, v104, v105
	v_cvt_pk_bf16_f32 v181, v106, v107
	global_store_dwordx2 v196, v[180:181], s[10:11] offset:3072
	s_nop 0
	v_mul_f32_e32 v108, v108, v210
	v_mul_f32_e32 v108, v12, v108
	v_fma_f32 v108, v156, v108, v172
	v_mul_f32_e32 v109, v109, v210
	v_mul_f32_e32 v109, v13, v109
	v_fma_f32 v109, v157, v109, v173
	v_mul_f32_e32 v110, v110, v210
	v_mul_f32_e32 v110, v14, v110
	v_fma_f32 v110, v158, v110, v174
	v_mul_f32_e32 v111, v111, v210
	v_mul_f32_e32 v111, v15, v111
	v_fma_f32 v111, v159, v111, v175
	v_cvt_pk_bf16_f32 v180, v108, v109
	v_cvt_pk_bf16_f32 v181, v110, v111
	global_store_dwordx2 v196, v[180:181], s[10:11] offset:3584
	s_nop 0
	s_add_u32 s14, s14, 0x2000
	s_addc_u32 s15, s15, 0
	global_load_dwordx4 v[80:83], v194, s[14:15]
	global_load_dwordx4 v[84:87], v194, s[14:15] offset:1024
	global_load_dwordx4 v[88:91], v194, s[14:15] offset:2048
	global_load_dwordx4 v[92:95], v194, s[14:15] offset:3072
	global_load_dwordx4 v[96:99], v195, s[14:15]
	global_load_dwordx4 v[100:103], v195, s[14:15] offset:1024
	global_load_dwordx4 v[104:107], v195, s[14:15] offset:2048
	global_load_dwordx4 v[108:111], v195, s[14:15] offset:3072
	s_waitcnt vmcnt(48)
	v_pk_mul_f32 v[178:179], v[112:113], v[112:113]
	v_pk_fma_f32 v[178:179], v[114:115], v[114:115], v[178:179]
	v_pk_fma_f32 v[178:179], v[116:117], v[116:117], v[178:179]
	v_pk_fma_f32 v[178:179], v[118:119], v[118:119], v[178:179]
	v_pk_fma_f32 v[178:179], v[120:121], v[120:121], v[178:179]
	v_pk_fma_f32 v[178:179], v[122:123], v[122:123], v[178:179]
	v_pk_fma_f32 v[178:179], v[124:125], v[124:125], v[178:179]
	v_pk_fma_f32 v[178:179], v[126:127], v[126:127], v[178:179]
	v_pk_mul_f32 v[180:181], v[128:129], v[128:129]
	v_pk_fma_f32 v[180:181], v[130:131], v[130:131], v[180:181]
	v_pk_fma_f32 v[180:181], v[132:133], v[132:133], v[180:181]
	v_pk_fma_f32 v[180:181], v[134:135], v[134:135], v[180:181]
	v_pk_fma_f32 v[180:181], v[136:137], v[136:137], v[180:181]
	v_pk_fma_f32 v[180:181], v[138:139], v[138:139], v[180:181]
	v_pk_fma_f32 v[180:181], v[140:141], v[140:141], v[180:181]
	v_pk_fma_f32 v[180:181], v[142:143], v[142:143], v[180:181]
	v_add_f32_e32 v176, v178, v179
	v_add_f32_e32 v177, v180, v181
	ds_bpermute_b32 v178, v198, v176
	ds_bpermute_b32 v179, v198, v177
	s_waitcnt lgkmcnt(0)
	v_add_f32_e32 v176, v176, v178
	v_add_f32_e32 v177, v177, v179
	ds_bpermute_b32 v178, v199, v176
	ds_bpermute_b32 v179, v199, v177
	s_waitcnt lgkmcnt(0)
	v_add_f32_e32 v176, v176, v178
	v_add_f32_e32 v177, v177, v179
	ds_bpermute_b32 v178, v200, v176
	ds_bpermute_b32 v179, v200, v177
	s_waitcnt lgkmcnt(0)
	v_add_f32_e32 v176, v176, v178
	v_add_f32_e32 v177, v177, v179
	ds_bpermute_b32 v178, v201, v176
	ds_bpermute_b32 v179, v201, v177
	s_waitcnt lgkmcnt(0)
	v_add_f32_e32 v176, v176, v178
	v_add_f32_e32 v177, v177, v179
	ds_bpermute_b32 v178, v202, v176
	ds_bpermute_b32 v179, v202, v177
	s_waitcnt lgkmcnt(0)
	v_add_f32_e32 v176, v176, v178
	v_add_f32_e32 v177, v177, v179
	ds_bpermute_b32 v178, v203, v176
	ds_bpermute_b32 v179, v203, v177
	s_waitcnt lgkmcnt(0)
	v_add_f32_e32 v176, v176, v178
	v_add_f32_e32 v177, v177, v179
	v_fmamk_f32 v176, v176, 0x3a800000, v208
	v_mul_f32_e32 v178, 0x4b800000, v176
	v_cmp_gt_f32_e32 vcc, s27, v176
	s_nop 1
	v_cndmask_b32_e32 v176, v176, v178, vcc
	v_rsq_f32_e32 v209, v176
	s_nop 0
	v_mul_f32_e32 v178, 0x45800000, v209
	v_cndmask_b32_e32 v209, v209, v178, vcc
	v_fmamk_f32 v177, v177, 0x3a800000, v208
	v_mul_f32_e32 v178, 0x4b800000, v177
	v_cmp_gt_f32_e32 vcc, s27, v177
	s_nop 1
	v_cndmask_b32_e32 v177, v177, v178, vcc
	v_rsq_f32_e32 v210, v177
	s_nop 0
	v_mul_f32_e32 v178, 0x45800000, v210
	v_cndmask_b32_e32 v210, v210, v178, vcc
	s_add_u32 s10, s10, 0x1000
	s_addc_u32 s11, s11, 0
	v_mul_f32_e32 v112, v112, v209
	v_mul_f32_e32 v112, v0, v112
	v_fma_f32 v112, v144, v112, v160
	v_mul_f32_e32 v113, v113, v209
	v_mul_f32_e32 v113, v1, v113
	v_fma_f32 v113, v145, v113, v161
	v_mul_f32_e32 v114, v114, v209
	v_mul_f32_e32 v114, v2, v114
	v_fma_f32 v114, v146, v114, v162
	v_mul_f32_e32 v115, v115, v209
	v_mul_f32_e32 v115, v3, v115
	v_fma_f32 v115, v147, v115, v163
	v_cvt_pk_bf16_f32 v180, v112, v113
	v_cvt_pk_bf16_f32 v181, v114, v115
	global_store_dwordx2 v196, v[180:181], s[10:11]
	s_nop 0
	v_mul_f32_e32 v116, v116, v209
	v_mul_f32_e32 v116, v4, v116
	v_fma_f32 v116, v148, v116, v164
	v_mul_f32_e32 v117, v117, v209
	v_mul_f32_e32 v117, v5, v117
	v_fma_f32 v117, v149, v117, v165
	v_mul_f32_e32 v118, v118, v209
	v_mul_f32_e32 v118, v6, v118
	v_fma_f32 v118, v150, v118, v166
	v_mul_f32_e32 v119, v119, v209
	v_mul_f32_e32 v119, v7, v119
	v_fma_f32 v119, v151, v119, v167
	v_cvt_pk_bf16_f32 v180, v116, v117
	v_cvt_pk_bf16_f32 v181, v118, v119
	global_store_dwordx2 v196, v[180:181], s[10:11] offset:512
	s_nop 0
	v_mul_f32_e32 v120, v120, v209
	v_mul_f32_e32 v120, v8, v120
	v_fma_f32 v120, v152, v120, v168
	v_mul_f32_e32 v121, v121, v209
	v_mul_f32_e32 v121, v9, v121
	v_fma_f32 v121, v153, v121, v169
	v_mul_f32_e32 v122, v122, v209
	v_mul_f32_e32 v122, v10, v122
	v_fma_f32 v122, v154, v122, v170
	v_mul_f32_e32 v123, v123, v209
	v_mul_f32_e32 v123, v11, v123
	v_fma_f32 v123, v155, v123, v171
	v_cvt_pk_bf16_f32 v180, v120, v121
	v_cvt_pk_bf16_f32 v181, v122, v123
	global_store_dwordx2 v196, v[180:181], s[10:11] offset:1024
	s_nop 0
	v_mul_f32_e32 v124, v124, v209
	v_mul_f32_e32 v124, v12, v124
	v_fma_f32 v124, v156, v124, v172
	v_mul_f32_e32 v125, v125, v209
	v_mul_f32_e32 v125, v13, v125
	v_fma_f32 v125, v157, v125, v173
	v_mul_f32_e32 v126, v126, v209
	v_mul_f32_e32 v126, v14, v126
	v_fma_f32 v126, v158, v126, v174
	v_mul_f32_e32 v127, v127, v209
	v_mul_f32_e32 v127, v15, v127
	v_fma_f32 v127, v159, v127, v175
	v_cvt_pk_bf16_f32 v180, v124, v125
	v_cvt_pk_bf16_f32 v181, v126, v127
	global_store_dwordx2 v196, v[180:181], s[10:11] offset:1536
	s_nop 0
	v_mul_f32_e32 v128, v128, v210
	v_mul_f32_e32 v128, v0, v128
	v_fma_f32 v128, v144, v128, v160
	v_mul_f32_e32 v129, v129, v210
	v_mul_f32_e32 v129, v1, v129
	v_fma_f32 v129, v145, v129, v161
	v_mul_f32_e32 v130, v130, v210
	v_mul_f32_e32 v130, v2, v130
	v_fma_f32 v130, v146, v130, v162
	v_mul_f32_e32 v131, v131, v210
	v_mul_f32_e32 v131, v3, v131
	v_fma_f32 v131, v147, v131, v163
	v_cvt_pk_bf16_f32 v180, v128, v129
	v_cvt_pk_bf16_f32 v181, v130, v131
	global_store_dwordx2 v196, v[180:181], s[10:11] offset:2048
	s_nop 0
	v_mul_f32_e32 v132, v132, v210
	v_mul_f32_e32 v132, v4, v132
	v_fma_f32 v132, v148, v132, v164
	v_mul_f32_e32 v133, v133, v210
	v_mul_f32_e32 v133, v5, v133
	v_fma_f32 v133, v149, v133, v165
	v_mul_f32_e32 v134, v134, v210
	v_mul_f32_e32 v134, v6, v134
	v_fma_f32 v134, v150, v134, v166
	v_mul_f32_e32 v135, v135, v210
	v_mul_f32_e32 v135, v7, v135
	v_fma_f32 v135, v151, v135, v167
	v_cvt_pk_bf16_f32 v180, v132, v133
	v_cvt_pk_bf16_f32 v181, v134, v135
	global_store_dwordx2 v196, v[180:181], s[10:11] offset:2560
	s_nop 0
	v_mul_f32_e32 v136, v136, v210
	v_mul_f32_e32 v136, v8, v136
	v_fma_f32 v136, v152, v136, v168
	v_mul_f32_e32 v137, v137, v210
	v_mul_f32_e32 v137, v9, v137
	v_fma_f32 v137, v153, v137, v169
	v_mul_f32_e32 v138, v138, v210
	v_mul_f32_e32 v138, v10, v138
	v_fma_f32 v138, v154, v138, v170
	v_mul_f32_e32 v139, v139, v210
	v_mul_f32_e32 v139, v11, v139
	v_fma_f32 v139, v155, v139, v171
	v_cvt_pk_bf16_f32 v180, v136, v137
	v_cvt_pk_bf16_f32 v181, v138, v139
	global_store_dwordx2 v196, v[180:181], s[10:11] offset:3072
	s_nop 0
	v_mul_f32_e32 v140, v140, v210
	v_mul_f32_e32 v140, v12, v140
	v_fma_f32 v140, v156, v140, v172
	v_mul_f32_e32 v141, v141, v210
	v_mul_f32_e32 v141, v13, v141
	v_fma_f32 v141, v157, v141, v173
	v_mul_f32_e32 v142, v142, v210
	v_mul_f32_e32 v142, v14, v142
	v_fma_f32 v142, v158, v142, v174
	v_mul_f32_e32 v143, v143, v210
	v_mul_f32_e32 v143, v15, v143
	v_fma_f32 v143, v159, v143, v175
	v_cvt_pk_bf16_f32 v180, v140, v141
	v_cvt_pk_bf16_f32 v181, v142, v143
	global_store_dwordx2 v196, v[180:181], s[10:11] offset:3584
	s_nop 0
	s_add_u32 s14, s14, 0x2000
	s_addc_u32 s15, s15, 0
	global_load_dwordx4 v[112:115], v194, s[14:15]
	global_load_dwordx4 v[116:119], v194, s[14:15] offset:1024
	global_load_dwordx4 v[120:123], v194, s[14:15] offset:2048
	global_load_dwordx4 v[124:127], v194, s[14:15] offset:3072
	global_load_dwordx4 v[128:131], v195, s[14:15]
	global_load_dwordx4 v[132:135], v195, s[14:15] offset:1024
	global_load_dwordx4 v[136:139], v195, s[14:15] offset:2048
	global_load_dwordx4 v[140:143], v195, s[14:15] offset:3072
	s_waitcnt vmcnt(48)
	v_pk_mul_f32 v[178:179], v[16:17], v[16:17]
	v_pk_fma_f32 v[178:179], v[18:19], v[18:19], v[178:179]
	v_pk_fma_f32 v[178:179], v[20:21], v[20:21], v[178:179]
	v_pk_fma_f32 v[178:179], v[22:23], v[22:23], v[178:179]
	v_pk_fma_f32 v[178:179], v[24:25], v[24:25], v[178:179]
	v_pk_fma_f32 v[178:179], v[26:27], v[26:27], v[178:179]
	v_pk_fma_f32 v[178:179], v[28:29], v[28:29], v[178:179]
	v_pk_fma_f32 v[178:179], v[30:31], v[30:31], v[178:179]
	v_pk_mul_f32 v[180:181], v[32:33], v[32:33]
	v_pk_fma_f32 v[180:181], v[34:35], v[34:35], v[180:181]
	v_pk_fma_f32 v[180:181], v[36:37], v[36:37], v[180:181]
	v_pk_fma_f32 v[180:181], v[38:39], v[38:39], v[180:181]
	v_pk_fma_f32 v[180:181], v[40:41], v[40:41], v[180:181]
	v_pk_fma_f32 v[180:181], v[42:43], v[42:43], v[180:181]
	v_pk_fma_f32 v[180:181], v[44:45], v[44:45], v[180:181]
	v_pk_fma_f32 v[180:181], v[46:47], v[46:47], v[180:181]
	v_add_f32_e32 v176, v178, v179
	v_add_f32_e32 v177, v180, v181
	ds_bpermute_b32 v178, v198, v176
	ds_bpermute_b32 v179, v198, v177
	s_waitcnt lgkmcnt(0)
	v_add_f32_e32 v176, v176, v178
	v_add_f32_e32 v177, v177, v179
	ds_bpermute_b32 v178, v199, v176
	ds_bpermute_b32 v179, v199, v177
	s_waitcnt lgkmcnt(0)
	v_add_f32_e32 v176, v176, v178
	v_add_f32_e32 v177, v177, v179
	ds_bpermute_b32 v178, v200, v176
	ds_bpermute_b32 v179, v200, v177
	s_waitcnt lgkmcnt(0)
	v_add_f32_e32 v176, v176, v178
	v_add_f32_e32 v177, v177, v179
	ds_bpermute_b32 v178, v201, v176
	ds_bpermute_b32 v179, v201, v177
	s_waitcnt lgkmcnt(0)
	v_add_f32_e32 v176, v176, v178
	v_add_f32_e32 v177, v177, v179
	ds_bpermute_b32 v178, v202, v176
	ds_bpermute_b32 v179, v202, v177
	s_waitcnt lgkmcnt(0)
	v_add_f32_e32 v176, v176, v178
	v_add_f32_e32 v177, v177, v179
	ds_bpermute_b32 v178, v203, v176
	ds_bpermute_b32 v179, v203, v177
	s_waitcnt lgkmcnt(0)
	v_add_f32_e32 v176, v176, v178
	v_add_f32_e32 v177, v177, v179
	v_fmamk_f32 v176, v176, 0x3a800000, v208
	v_mul_f32_e32 v178, 0x4b800000, v176
	v_cmp_gt_f32_e32 vcc, s27, v176
	s_nop 1
	v_cndmask_b32_e32 v176, v176, v178, vcc
	v_rsq_f32_e32 v209, v176
	s_nop 0
	v_mul_f32_e32 v178, 0x45800000, v209
	v_cndmask_b32_e32 v209, v209, v178, vcc
	v_fmamk_f32 v177, v177, 0x3a800000, v208
	v_mul_f32_e32 v178, 0x4b800000, v177
	v_cmp_gt_f32_e32 vcc, s27, v177
	s_nop 1
	v_cndmask_b32_e32 v177, v177, v178, vcc
	v_rsq_f32_e32 v210, v177
	s_nop 0
	v_mul_f32_e32 v178, 0x45800000, v210
	v_cndmask_b32_e32 v210, v210, v178, vcc
	s_add_u32 s10, s10, 0x1000
	s_addc_u32 s11, s11, 0
	v_mul_f32_e32 v16, v16, v209
	v_mul_f32_e32 v16, v0, v16
	v_fma_f32 v16, v144, v16, v160
	v_mul_f32_e32 v17, v17, v209
	v_mul_f32_e32 v17, v1, v17
	v_fma_f32 v17, v145, v17, v161
	v_mul_f32_e32 v18, v18, v209
	v_mul_f32_e32 v18, v2, v18
	v_fma_f32 v18, v146, v18, v162
	v_mul_f32_e32 v19, v19, v209
	v_mul_f32_e32 v19, v3, v19
	v_fma_f32 v19, v147, v19, v163
	v_cvt_pk_bf16_f32 v180, v16, v17
	v_cvt_pk_bf16_f32 v181, v18, v19
	global_store_dwordx2 v196, v[180:181], s[10:11]
	s_nop 0
	v_mul_f32_e32 v20, v20, v209
	v_mul_f32_e32 v20, v4, v20
	v_fma_f32 v20, v148, v20, v164
	v_mul_f32_e32 v21, v21, v209
	v_mul_f32_e32 v21, v5, v21
	v_fma_f32 v21, v149, v21, v165
	v_mul_f32_e32 v22, v22, v209
	v_mul_f32_e32 v22, v6, v22
	v_fma_f32 v22, v150, v22, v166
	v_mul_f32_e32 v23, v23, v209
	v_mul_f32_e32 v23, v7, v23
	v_fma_f32 v23, v151, v23, v167
	v_cvt_pk_bf16_f32 v180, v20, v21
	v_cvt_pk_bf16_f32 v181, v22, v23
	global_store_dwordx2 v196, v[180:181], s[10:11] offset:512
	s_nop 0
	v_mul_f32_e32 v24, v24, v209
	v_mul_f32_e32 v24, v8, v24
	v_fma_f32 v24, v152, v24, v168
	v_mul_f32_e32 v25, v25, v209
	v_mul_f32_e32 v25, v9, v25
	v_fma_f32 v25, v153, v25, v169
	v_mul_f32_e32 v26, v26, v209
	v_mul_f32_e32 v26, v10, v26
	v_fma_f32 v26, v154, v26, v170
	v_mul_f32_e32 v27, v27, v209
	v_mul_f32_e32 v27, v11, v27
	v_fma_f32 v27, v155, v27, v171
	v_cvt_pk_bf16_f32 v180, v24, v25
	v_cvt_pk_bf16_f32 v181, v26, v27
	global_store_dwordx2 v196, v[180:181], s[10:11] offset:1024
	s_nop 0
	v_mul_f32_e32 v28, v28, v209
	v_mul_f32_e32 v28, v12, v28
	v_fma_f32 v28, v156, v28, v172
	v_mul_f32_e32 v29, v29, v209
	v_mul_f32_e32 v29, v13, v29
	v_fma_f32 v29, v157, v29, v173
	v_mul_f32_e32 v30, v30, v209
	v_mul_f32_e32 v30, v14, v30
	v_fma_f32 v30, v158, v30, v174
	v_mul_f32_e32 v31, v31, v209
	v_mul_f32_e32 v31, v15, v31
	v_fma_f32 v31, v159, v31, v175
	v_cvt_pk_bf16_f32 v180, v28, v29
	v_cvt_pk_bf16_f32 v181, v30, v31
	global_store_dwordx2 v196, v[180:181], s[10:11] offset:1536
	s_nop 0
	v_mul_f32_e32 v32, v32, v210
	v_mul_f32_e32 v32, v0, v32
	v_fma_f32 v32, v144, v32, v160
	v_mul_f32_e32 v33, v33, v210
	v_mul_f32_e32 v33, v1, v33
	v_fma_f32 v33, v145, v33, v161
	v_mul_f32_e32 v34, v34, v210
	v_mul_f32_e32 v34, v2, v34
	v_fma_f32 v34, v146, v34, v162
	v_mul_f32_e32 v35, v35, v210
	v_mul_f32_e32 v35, v3, v35
	v_fma_f32 v35, v147, v35, v163
	v_cvt_pk_bf16_f32 v180, v32, v33
	v_cvt_pk_bf16_f32 v181, v34, v35
	global_store_dwordx2 v196, v[180:181], s[10:11] offset:2048
	s_nop 0
	v_mul_f32_e32 v36, v36, v210
	v_mul_f32_e32 v36, v4, v36
	v_fma_f32 v36, v148, v36, v164
	v_mul_f32_e32 v37, v37, v210
	v_mul_f32_e32 v37, v5, v37
	v_fma_f32 v37, v149, v37, v165
	v_mul_f32_e32 v38, v38, v210
	v_mul_f32_e32 v38, v6, v38
	v_fma_f32 v38, v150, v38, v166
	v_mul_f32_e32 v39, v39, v210
	v_mul_f32_e32 v39, v7, v39
	v_fma_f32 v39, v151, v39, v167
	v_cvt_pk_bf16_f32 v180, v36, v37
	v_cvt_pk_bf16_f32 v181, v38, v39
	global_store_dwordx2 v196, v[180:181], s[10:11] offset:2560
	s_nop 0
	v_mul_f32_e32 v40, v40, v210
	v_mul_f32_e32 v40, v8, v40
	v_fma_f32 v40, v152, v40, v168
	v_mul_f32_e32 v41, v41, v210
	v_mul_f32_e32 v41, v9, v41
	v_fma_f32 v41, v153, v41, v169
	v_mul_f32_e32 v42, v42, v210
	v_mul_f32_e32 v42, v10, v42
	v_fma_f32 v42, v154, v42, v170
	v_mul_f32_e32 v43, v43, v210
	v_mul_f32_e32 v43, v11, v43
	v_fma_f32 v43, v155, v43, v171
	v_cvt_pk_bf16_f32 v180, v40, v41
	v_cvt_pk_bf16_f32 v181, v42, v43
	global_store_dwordx2 v196, v[180:181], s[10:11] offset:3072
	s_nop 0
	v_mul_f32_e32 v44, v44, v210
	v_mul_f32_e32 v44, v12, v44
	v_fma_f32 v44, v156, v44, v172
	v_mul_f32_e32 v45, v45, v210
	v_mul_f32_e32 v45, v13, v45
	v_fma_f32 v45, v157, v45, v173
	v_mul_f32_e32 v46, v46, v210
	v_mul_f32_e32 v46, v14, v46
	v_fma_f32 v46, v158, v46, v174
	v_mul_f32_e32 v47, v47, v210
	v_mul_f32_e32 v47, v15, v47
	v_fma_f32 v47, v159, v47, v175
	v_cvt_pk_bf16_f32 v180, v44, v45
	v_cvt_pk_bf16_f32 v181, v46, v47
	global_store_dwordx2 v196, v[180:181], s[10:11] offset:3584
	s_nop 0
	s_add_u32 s14, s14, 0x2000
	s_addc_u32 s15, s15, 0
	global_load_dwordx4 v[16:19], v194, s[14:15]
	global_load_dwordx4 v[20:23], v194, s[14:15] offset:1024
	global_load_dwordx4 v[24:27], v194, s[14:15] offset:2048
	global_load_dwordx4 v[28:31], v194, s[14:15] offset:3072
	global_load_dwordx4 v[32:35], v195, s[14:15]
	global_load_dwordx4 v[36:39], v195, s[14:15] offset:1024
	global_load_dwordx4 v[40:43], v195, s[14:15] offset:2048
	global_load_dwordx4 v[44:47], v195, s[14:15] offset:3072
	s_waitcnt vmcnt(48)
	v_pk_mul_f32 v[178:179], v[48:49], v[48:49]
	v_pk_fma_f32 v[178:179], v[50:51], v[50:51], v[178:179]
	v_pk_fma_f32 v[178:179], v[52:53], v[52:53], v[178:179]
	v_pk_fma_f32 v[178:179], v[54:55], v[54:55], v[178:179]
	v_pk_fma_f32 v[178:179], v[56:57], v[56:57], v[178:179]
	v_pk_fma_f32 v[178:179], v[58:59], v[58:59], v[178:179]
	v_pk_fma_f32 v[178:179], v[60:61], v[60:61], v[178:179]
	v_pk_fma_f32 v[178:179], v[62:63], v[62:63], v[178:179]
	v_pk_mul_f32 v[180:181], v[64:65], v[64:65]
	v_pk_fma_f32 v[180:181], v[66:67], v[66:67], v[180:181]
	v_pk_fma_f32 v[180:181], v[68:69], v[68:69], v[180:181]
	v_pk_fma_f32 v[180:181], v[70:71], v[70:71], v[180:181]
	v_pk_fma_f32 v[180:181], v[72:73], v[72:73], v[180:181]
	v_pk_fma_f32 v[180:181], v[74:75], v[74:75], v[180:181]
	v_pk_fma_f32 v[180:181], v[76:77], v[76:77], v[180:181]
	v_pk_fma_f32 v[180:181], v[78:79], v[78:79], v[180:181]
	v_add_f32_e32 v176, v178, v179
	v_add_f32_e32 v177, v180, v181
	ds_bpermute_b32 v178, v198, v176
	ds_bpermute_b32 v179, v198, v177
	s_waitcnt lgkmcnt(0)
	v_add_f32_e32 v176, v176, v178
	v_add_f32_e32 v177, v177, v179
	ds_bpermute_b32 v178, v199, v176
	ds_bpermute_b32 v179, v199, v177
	s_waitcnt lgkmcnt(0)
	v_add_f32_e32 v176, v176, v178
	v_add_f32_e32 v177, v177, v179
	ds_bpermute_b32 v178, v200, v176
	ds_bpermute_b32 v179, v200, v177
	s_waitcnt lgkmcnt(0)
	v_add_f32_e32 v176, v176, v178
	v_add_f32_e32 v177, v177, v179
	ds_bpermute_b32 v178, v201, v176
	ds_bpermute_b32 v179, v201, v177
	s_waitcnt lgkmcnt(0)
	v_add_f32_e32 v176, v176, v178
	v_add_f32_e32 v177, v177, v179
	ds_bpermute_b32 v178, v202, v176
	ds_bpermute_b32 v179, v202, v177
	s_waitcnt lgkmcnt(0)
	v_add_f32_e32 v176, v176, v178
	v_add_f32_e32 v177, v177, v179
	ds_bpermute_b32 v178, v203, v176
	ds_bpermute_b32 v179, v203, v177
	s_waitcnt lgkmcnt(0)
	v_add_f32_e32 v176, v176, v178
	v_add_f32_e32 v177, v177, v179
	v_fmamk_f32 v176, v176, 0x3a800000, v208
	v_mul_f32_e32 v178, 0x4b800000, v176
	v_cmp_gt_f32_e32 vcc, s27, v176
	s_nop 1
	v_cndmask_b32_e32 v176, v176, v178, vcc
	v_rsq_f32_e32 v209, v176
	s_nop 0
	v_mul_f32_e32 v178, 0x45800000, v209
	v_cndmask_b32_e32 v209, v209, v178, vcc
	v_fmamk_f32 v177, v177, 0x3a800000, v208
	v_mul_f32_e32 v178, 0x4b800000, v177
	v_cmp_gt_f32_e32 vcc, s27, v177
	s_nop 1
	v_cndmask_b32_e32 v177, v177, v178, vcc
	v_rsq_f32_e32 v210, v177
	s_nop 0
	v_mul_f32_e32 v178, 0x45800000, v210
	v_cndmask_b32_e32 v210, v210, v178, vcc
	s_add_u32 s10, s10, 0x1000
	s_addc_u32 s11, s11, 0
	v_mul_f32_e32 v48, v48, v209
	v_mul_f32_e32 v48, v0, v48
	v_fma_f32 v48, v144, v48, v160
	v_mul_f32_e32 v49, v49, v209
	v_mul_f32_e32 v49, v1, v49
	v_fma_f32 v49, v145, v49, v161
	v_mul_f32_e32 v50, v50, v209
	v_mul_f32_e32 v50, v2, v50
	v_fma_f32 v50, v146, v50, v162
	v_mul_f32_e32 v51, v51, v209
	v_mul_f32_e32 v51, v3, v51
	v_fma_f32 v51, v147, v51, v163
	v_cvt_pk_bf16_f32 v180, v48, v49
	v_cvt_pk_bf16_f32 v181, v50, v51
	global_store_dwordx2 v196, v[180:181], s[10:11]
	s_nop 0
	v_mul_f32_e32 v52, v52, v209
	v_mul_f32_e32 v52, v4, v52
	v_fma_f32 v52, v148, v52, v164
	v_mul_f32_e32 v53, v53, v209
	v_mul_f32_e32 v53, v5, v53
	v_fma_f32 v53, v149, v53, v165
	v_mul_f32_e32 v54, v54, v209
	v_mul_f32_e32 v54, v6, v54
	v_fma_f32 v54, v150, v54, v166
	v_mul_f32_e32 v55, v55, v209
	v_mul_f32_e32 v55, v7, v55
	v_fma_f32 v55, v151, v55, v167
	v_cvt_pk_bf16_f32 v180, v52, v53
	v_cvt_pk_bf16_f32 v181, v54, v55
	global_store_dwordx2 v196, v[180:181], s[10:11] offset:512
	s_nop 0
	v_mul_f32_e32 v56, v56, v209
	v_mul_f32_e32 v56, v8, v56
	v_fma_f32 v56, v152, v56, v168
	v_mul_f32_e32 v57, v57, v209
	v_mul_f32_e32 v57, v9, v57
	v_fma_f32 v57, v153, v57, v169
	v_mul_f32_e32 v58, v58, v209
	v_mul_f32_e32 v58, v10, v58
	v_fma_f32 v58, v154, v58, v170
	v_mul_f32_e32 v59, v59, v209
	v_mul_f32_e32 v59, v11, v59
	v_fma_f32 v59, v155, v59, v171
	v_cvt_pk_bf16_f32 v180, v56, v57
	v_cvt_pk_bf16_f32 v181, v58, v59
	global_store_dwordx2 v196, v[180:181], s[10:11] offset:1024
	s_nop 0
	v_mul_f32_e32 v60, v60, v209
	v_mul_f32_e32 v60, v12, v60
	v_fma_f32 v60, v156, v60, v172
	v_mul_f32_e32 v61, v61, v209
	v_mul_f32_e32 v61, v13, v61
	v_fma_f32 v61, v157, v61, v173
	v_mul_f32_e32 v62, v62, v209
	v_mul_f32_e32 v62, v14, v62
	v_fma_f32 v62, v158, v62, v174
	v_mul_f32_e32 v63, v63, v209
	v_mul_f32_e32 v63, v15, v63
	v_fma_f32 v63, v159, v63, v175
	v_cvt_pk_bf16_f32 v180, v60, v61
	v_cvt_pk_bf16_f32 v181, v62, v63
	global_store_dwordx2 v196, v[180:181], s[10:11] offset:1536
	s_nop 0
	v_mul_f32_e32 v64, v64, v210
	v_mul_f32_e32 v64, v0, v64
	v_fma_f32 v64, v144, v64, v160
	v_mul_f32_e32 v65, v65, v210
	v_mul_f32_e32 v65, v1, v65
	v_fma_f32 v65, v145, v65, v161
	v_mul_f32_e32 v66, v66, v210
	v_mul_f32_e32 v66, v2, v66
	v_fma_f32 v66, v146, v66, v162
	v_mul_f32_e32 v67, v67, v210
	v_mul_f32_e32 v67, v3, v67
	v_fma_f32 v67, v147, v67, v163
	v_cvt_pk_bf16_f32 v180, v64, v65
	v_cvt_pk_bf16_f32 v181, v66, v67
	global_store_dwordx2 v196, v[180:181], s[10:11] offset:2048
	s_nop 0
	v_mul_f32_e32 v68, v68, v210
	v_mul_f32_e32 v68, v4, v68
	v_fma_f32 v68, v148, v68, v164
	v_mul_f32_e32 v69, v69, v210
	v_mul_f32_e32 v69, v5, v69
	v_fma_f32 v69, v149, v69, v165
	v_mul_f32_e32 v70, v70, v210
	v_mul_f32_e32 v70, v6, v70
	v_fma_f32 v70, v150, v70, v166
	v_mul_f32_e32 v71, v71, v210
	v_mul_f32_e32 v71, v7, v71
	v_fma_f32 v71, v151, v71, v167
	v_cvt_pk_bf16_f32 v180, v68, v69
	v_cvt_pk_bf16_f32 v181, v70, v71
	global_store_dwordx2 v196, v[180:181], s[10:11] offset:2560
	s_nop 0
	v_mul_f32_e32 v72, v72, v210
	v_mul_f32_e32 v72, v8, v72
	v_fma_f32 v72, v152, v72, v168
	v_mul_f32_e32 v73, v73, v210
	v_mul_f32_e32 v73, v9, v73
	v_fma_f32 v73, v153, v73, v169
	v_mul_f32_e32 v74, v74, v210
	v_mul_f32_e32 v74, v10, v74
	v_fma_f32 v74, v154, v74, v170
	v_mul_f32_e32 v75, v75, v210
	v_mul_f32_e32 v75, v11, v75
	v_fma_f32 v75, v155, v75, v171
	v_cvt_pk_bf16_f32 v180, v72, v73
	v_cvt_pk_bf16_f32 v181, v74, v75
	global_store_dwordx2 v196, v[180:181], s[10:11] offset:3072
	s_nop 0
	v_mul_f32_e32 v76, v76, v210
	v_mul_f32_e32 v76, v12, v76
	v_fma_f32 v76, v156, v76, v172
	v_mul_f32_e32 v77, v77, v210
	v_mul_f32_e32 v77, v13, v77
	v_fma_f32 v77, v157, v77, v173
	v_mul_f32_e32 v78, v78, v210
	v_mul_f32_e32 v78, v14, v78
	v_fma_f32 v78, v158, v78, v174
	v_mul_f32_e32 v79, v79, v210
	v_mul_f32_e32 v79, v15, v79
	v_fma_f32 v79, v159, v79, v175
	v_cvt_pk_bf16_f32 v180, v76, v77
	v_cvt_pk_bf16_f32 v181, v78, v79
	global_store_dwordx2 v196, v[180:181], s[10:11] offset:3584
	s_nop 0
	s_add_u32 s14, s14, 0x2000
	s_addc_u32 s15, s15, 0
	global_load_dwordx4 v[48:51], v194, s[14:15]
	global_load_dwordx4 v[52:55], v194, s[14:15] offset:1024
	global_load_dwordx4 v[56:59], v194, s[14:15] offset:2048
	global_load_dwordx4 v[60:63], v194, s[14:15] offset:3072
	global_load_dwordx4 v[64:67], v195, s[14:15]
	global_load_dwordx4 v[68:71], v195, s[14:15] offset:1024
	global_load_dwordx4 v[72:75], v195, s[14:15] offset:2048
	global_load_dwordx4 v[76:79], v195, s[14:15] offset:3072
	s_waitcnt vmcnt(48)
	v_pk_mul_f32 v[178:179], v[80:81], v[80:81]
	v_pk_fma_f32 v[178:179], v[82:83], v[82:83], v[178:179]
	v_pk_fma_f32 v[178:179], v[84:85], v[84:85], v[178:179]
	v_pk_fma_f32 v[178:179], v[86:87], v[86:87], v[178:179]
	v_pk_fma_f32 v[178:179], v[88:89], v[88:89], v[178:179]
	v_pk_fma_f32 v[178:179], v[90:91], v[90:91], v[178:179]
	v_pk_fma_f32 v[178:179], v[92:93], v[92:93], v[178:179]
	v_pk_fma_f32 v[178:179], v[94:95], v[94:95], v[178:179]
	v_pk_mul_f32 v[180:181], v[96:97], v[96:97]
	v_pk_fma_f32 v[180:181], v[98:99], v[98:99], v[180:181]
	v_pk_fma_f32 v[180:181], v[100:101], v[100:101], v[180:181]
	v_pk_fma_f32 v[180:181], v[102:103], v[102:103], v[180:181]
	v_pk_fma_f32 v[180:181], v[104:105], v[104:105], v[180:181]
	v_pk_fma_f32 v[180:181], v[106:107], v[106:107], v[180:181]
	v_pk_fma_f32 v[180:181], v[108:109], v[108:109], v[180:181]
	v_pk_fma_f32 v[180:181], v[110:111], v[110:111], v[180:181]
	v_add_f32_e32 v176, v178, v179
	v_add_f32_e32 v177, v180, v181
	ds_bpermute_b32 v178, v198, v176
	ds_bpermute_b32 v179, v198, v177
	s_waitcnt lgkmcnt(0)
	v_add_f32_e32 v176, v176, v178
	v_add_f32_e32 v177, v177, v179
	ds_bpermute_b32 v178, v199, v176
	ds_bpermute_b32 v179, v199, v177
	s_waitcnt lgkmcnt(0)
	v_add_f32_e32 v176, v176, v178
	v_add_f32_e32 v177, v177, v179
	ds_bpermute_b32 v178, v200, v176
	ds_bpermute_b32 v179, v200, v177
	s_waitcnt lgkmcnt(0)
	v_add_f32_e32 v176, v176, v178
	v_add_f32_e32 v177, v177, v179
	ds_bpermute_b32 v178, v201, v176
	ds_bpermute_b32 v179, v201, v177
	s_waitcnt lgkmcnt(0)
	v_add_f32_e32 v176, v176, v178
	v_add_f32_e32 v177, v177, v179
	ds_bpermute_b32 v178, v202, v176
	ds_bpermute_b32 v179, v202, v177
	s_waitcnt lgkmcnt(0)
	v_add_f32_e32 v176, v176, v178
	v_add_f32_e32 v177, v177, v179
	ds_bpermute_b32 v178, v203, v176
	ds_bpermute_b32 v179, v203, v177
	s_waitcnt lgkmcnt(0)
	v_add_f32_e32 v176, v176, v178
	v_add_f32_e32 v177, v177, v179
	v_fmamk_f32 v176, v176, 0x3a800000, v208
	v_mul_f32_e32 v178, 0x4b800000, v176
	v_cmp_gt_f32_e32 vcc, s27, v176
	s_nop 1
	v_cndmask_b32_e32 v176, v176, v178, vcc
	v_rsq_f32_e32 v209, v176
	s_nop 0
	v_mul_f32_e32 v178, 0x45800000, v209
	v_cndmask_b32_e32 v209, v209, v178, vcc
	v_fmamk_f32 v177, v177, 0x3a800000, v208
	v_mul_f32_e32 v178, 0x4b800000, v177
	v_cmp_gt_f32_e32 vcc, s27, v177
	s_nop 1
	v_cndmask_b32_e32 v177, v177, v178, vcc
	v_rsq_f32_e32 v210, v177
	s_nop 0
	v_mul_f32_e32 v178, 0x45800000, v210
	v_cndmask_b32_e32 v210, v210, v178, vcc
	s_add_u32 s10, s10, 0x1000
	s_addc_u32 s11, s11, 0
	v_mul_f32_e32 v80, v80, v209
	v_mul_f32_e32 v80, v0, v80
	v_fma_f32 v80, v144, v80, v160
	v_mul_f32_e32 v81, v81, v209
	v_mul_f32_e32 v81, v1, v81
	v_fma_f32 v81, v145, v81, v161
	v_mul_f32_e32 v82, v82, v209
	v_mul_f32_e32 v82, v2, v82
	v_fma_f32 v82, v146, v82, v162
	v_mul_f32_e32 v83, v83, v209
	v_mul_f32_e32 v83, v3, v83
	v_fma_f32 v83, v147, v83, v163
	v_cvt_pk_bf16_f32 v180, v80, v81
	v_cvt_pk_bf16_f32 v181, v82, v83
	global_store_dwordx2 v196, v[180:181], s[10:11]
	s_nop 0
	v_mul_f32_e32 v84, v84, v209
	v_mul_f32_e32 v84, v4, v84
	v_fma_f32 v84, v148, v84, v164
	v_mul_f32_e32 v85, v85, v209
	v_mul_f32_e32 v85, v5, v85
	v_fma_f32 v85, v149, v85, v165
	v_mul_f32_e32 v86, v86, v209
	v_mul_f32_e32 v86, v6, v86
	v_fma_f32 v86, v150, v86, v166
	v_mul_f32_e32 v87, v87, v209
	v_mul_f32_e32 v87, v7, v87
	v_fma_f32 v87, v151, v87, v167
	v_cvt_pk_bf16_f32 v180, v84, v85
	v_cvt_pk_bf16_f32 v181, v86, v87
	global_store_dwordx2 v196, v[180:181], s[10:11] offset:512
	s_nop 0
	v_mul_f32_e32 v88, v88, v209
	v_mul_f32_e32 v88, v8, v88
	v_fma_f32 v88, v152, v88, v168
	v_mul_f32_e32 v89, v89, v209
	v_mul_f32_e32 v89, v9, v89
	v_fma_f32 v89, v153, v89, v169
	v_mul_f32_e32 v90, v90, v209
	v_mul_f32_e32 v90, v10, v90
	v_fma_f32 v90, v154, v90, v170
	v_mul_f32_e32 v91, v91, v209
	v_mul_f32_e32 v91, v11, v91
	v_fma_f32 v91, v155, v91, v171
	v_cvt_pk_bf16_f32 v180, v88, v89
	v_cvt_pk_bf16_f32 v181, v90, v91
	global_store_dwordx2 v196, v[180:181], s[10:11] offset:1024
	s_nop 0
	v_mul_f32_e32 v92, v92, v209
	v_mul_f32_e32 v92, v12, v92
	v_fma_f32 v92, v156, v92, v172
	v_mul_f32_e32 v93, v93, v209
	v_mul_f32_e32 v93, v13, v93
	v_fma_f32 v93, v157, v93, v173
	v_mul_f32_e32 v94, v94, v209
	v_mul_f32_e32 v94, v14, v94
	v_fma_f32 v94, v158, v94, v174
	v_mul_f32_e32 v95, v95, v209
	v_mul_f32_e32 v95, v15, v95
	v_fma_f32 v95, v159, v95, v175
	v_cvt_pk_bf16_f32 v180, v92, v93
	v_cvt_pk_bf16_f32 v181, v94, v95
	global_store_dwordx2 v196, v[180:181], s[10:11] offset:1536
	s_nop 0
	v_mul_f32_e32 v96, v96, v210
	v_mul_f32_e32 v96, v0, v96
	v_fma_f32 v96, v144, v96, v160
	v_mul_f32_e32 v97, v97, v210
	v_mul_f32_e32 v97, v1, v97
	v_fma_f32 v97, v145, v97, v161
	v_mul_f32_e32 v98, v98, v210
	v_mul_f32_e32 v98, v2, v98
	v_fma_f32 v98, v146, v98, v162
	v_mul_f32_e32 v99, v99, v210
	v_mul_f32_e32 v99, v3, v99
	v_fma_f32 v99, v147, v99, v163
	v_cvt_pk_bf16_f32 v180, v96, v97
	v_cvt_pk_bf16_f32 v181, v98, v99
	global_store_dwordx2 v196, v[180:181], s[10:11] offset:2048
	s_nop 0
	v_mul_f32_e32 v100, v100, v210
	v_mul_f32_e32 v100, v4, v100
	v_fma_f32 v100, v148, v100, v164
	v_mul_f32_e32 v101, v101, v210
	v_mul_f32_e32 v101, v5, v101
	v_fma_f32 v101, v149, v101, v165
	v_mul_f32_e32 v102, v102, v210
	v_mul_f32_e32 v102, v6, v102
	v_fma_f32 v102, v150, v102, v166
	v_mul_f32_e32 v103, v103, v210
	v_mul_f32_e32 v103, v7, v103
	v_fma_f32 v103, v151, v103, v167
	v_cvt_pk_bf16_f32 v180, v100, v101
	v_cvt_pk_bf16_f32 v181, v102, v103
	global_store_dwordx2 v196, v[180:181], s[10:11] offset:2560
	s_nop 0
	v_mul_f32_e32 v104, v104, v210
	v_mul_f32_e32 v104, v8, v104
	v_fma_f32 v104, v152, v104, v168
	v_mul_f32_e32 v105, v105, v210
	v_mul_f32_e32 v105, v9, v105
	v_fma_f32 v105, v153, v105, v169
	v_mul_f32_e32 v106, v106, v210
	v_mul_f32_e32 v106, v10, v106
	v_fma_f32 v106, v154, v106, v170
	v_mul_f32_e32 v107, v107, v210
	v_mul_f32_e32 v107, v11, v107
	v_fma_f32 v107, v155, v107, v171
	v_cvt_pk_bf16_f32 v180, v104, v105
	v_cvt_pk_bf16_f32 v181, v106, v107
	global_store_dwordx2 v196, v[180:181], s[10:11] offset:3072
	s_nop 0
	v_mul_f32_e32 v108, v108, v210
	v_mul_f32_e32 v108, v12, v108
	v_fma_f32 v108, v156, v108, v172
	v_mul_f32_e32 v109, v109, v210
	v_mul_f32_e32 v109, v13, v109
	v_fma_f32 v109, v157, v109, v173
	v_mul_f32_e32 v110, v110, v210
	v_mul_f32_e32 v110, v14, v110
	v_fma_f32 v110, v158, v110, v174
	v_mul_f32_e32 v111, v111, v210
	v_mul_f32_e32 v111, v15, v111
	v_fma_f32 v111, v159, v111, v175
	v_cvt_pk_bf16_f32 v180, v108, v109
	v_cvt_pk_bf16_f32 v181, v110, v111
	global_store_dwordx2 v196, v[180:181], s[10:11] offset:3584
	s_nop 0
	s_add_u32 s14, s14, 0x2000
	s_addc_u32 s15, s15, 0
	global_load_dwordx4 v[80:83], v194, s[14:15]
	global_load_dwordx4 v[84:87], v194, s[14:15] offset:1024
	global_load_dwordx4 v[88:91], v194, s[14:15] offset:2048
	global_load_dwordx4 v[92:95], v194, s[14:15] offset:3072
	global_load_dwordx4 v[96:99], v195, s[14:15]
	global_load_dwordx4 v[100:103], v195, s[14:15] offset:1024
	global_load_dwordx4 v[104:107], v195, s[14:15] offset:2048
	global_load_dwordx4 v[108:111], v195, s[14:15] offset:3072
	s_waitcnt vmcnt(48)
	v_pk_mul_f32 v[178:179], v[112:113], v[112:113]
	v_pk_fma_f32 v[178:179], v[114:115], v[114:115], v[178:179]
	v_pk_fma_f32 v[178:179], v[116:117], v[116:117], v[178:179]
	v_pk_fma_f32 v[178:179], v[118:119], v[118:119], v[178:179]
	v_pk_fma_f32 v[178:179], v[120:121], v[120:121], v[178:179]
	v_pk_fma_f32 v[178:179], v[122:123], v[122:123], v[178:179]
	v_pk_fma_f32 v[178:179], v[124:125], v[124:125], v[178:179]
	v_pk_fma_f32 v[178:179], v[126:127], v[126:127], v[178:179]
	v_pk_mul_f32 v[180:181], v[128:129], v[128:129]
	v_pk_fma_f32 v[180:181], v[130:131], v[130:131], v[180:181]
	v_pk_fma_f32 v[180:181], v[132:133], v[132:133], v[180:181]
	v_pk_fma_f32 v[180:181], v[134:135], v[134:135], v[180:181]
	v_pk_fma_f32 v[180:181], v[136:137], v[136:137], v[180:181]
	v_pk_fma_f32 v[180:181], v[138:139], v[138:139], v[180:181]
	v_pk_fma_f32 v[180:181], v[140:141], v[140:141], v[180:181]
	v_pk_fma_f32 v[180:181], v[142:143], v[142:143], v[180:181]
	v_add_f32_e32 v176, v178, v179
	v_add_f32_e32 v177, v180, v181
	ds_bpermute_b32 v178, v198, v176
	ds_bpermute_b32 v179, v198, v177
	s_waitcnt lgkmcnt(0)
	v_add_f32_e32 v176, v176, v178
	v_add_f32_e32 v177, v177, v179
	ds_bpermute_b32 v178, v199, v176
	ds_bpermute_b32 v179, v199, v177
	s_waitcnt lgkmcnt(0)
	v_add_f32_e32 v176, v176, v178
	v_add_f32_e32 v177, v177, v179
	ds_bpermute_b32 v178, v200, v176
	ds_bpermute_b32 v179, v200, v177
	s_waitcnt lgkmcnt(0)
	v_add_f32_e32 v176, v176, v178
	v_add_f32_e32 v177, v177, v179
	ds_bpermute_b32 v178, v201, v176
	ds_bpermute_b32 v179, v201, v177
	s_waitcnt lgkmcnt(0)
	v_add_f32_e32 v176, v176, v178
	v_add_f32_e32 v177, v177, v179
	ds_bpermute_b32 v178, v202, v176
	ds_bpermute_b32 v179, v202, v177
	s_waitcnt lgkmcnt(0)
	v_add_f32_e32 v176, v176, v178
	v_add_f32_e32 v177, v177, v179
	ds_bpermute_b32 v178, v203, v176
	ds_bpermute_b32 v179, v203, v177
	s_waitcnt lgkmcnt(0)
	v_add_f32_e32 v176, v176, v178
	v_add_f32_e32 v177, v177, v179
	v_fmamk_f32 v176, v176, 0x3a800000, v208
	v_mul_f32_e32 v178, 0x4b800000, v176
	v_cmp_gt_f32_e32 vcc, s27, v176
	s_nop 1
	v_cndmask_b32_e32 v176, v176, v178, vcc
	v_rsq_f32_e32 v209, v176
	s_nop 0
	v_mul_f32_e32 v178, 0x45800000, v209
	v_cndmask_b32_e32 v209, v209, v178, vcc
	v_fmamk_f32 v177, v177, 0x3a800000, v208
	v_mul_f32_e32 v178, 0x4b800000, v177
	v_cmp_gt_f32_e32 vcc, s27, v177
	s_nop 1
	v_cndmask_b32_e32 v177, v177, v178, vcc
	v_rsq_f32_e32 v210, v177
	s_nop 0
	v_mul_f32_e32 v178, 0x45800000, v210
	v_cndmask_b32_e32 v210, v210, v178, vcc
	s_add_u32 s10, s10, 0x1000
	s_addc_u32 s11, s11, 0
	v_mul_f32_e32 v112, v112, v209
	v_mul_f32_e32 v112, v0, v112
	v_fma_f32 v112, v144, v112, v160
	v_mul_f32_e32 v113, v113, v209
	v_mul_f32_e32 v113, v1, v113
	v_fma_f32 v113, v145, v113, v161
	v_mul_f32_e32 v114, v114, v209
	v_mul_f32_e32 v114, v2, v114
	v_fma_f32 v114, v146, v114, v162
	v_mul_f32_e32 v115, v115, v209
	v_mul_f32_e32 v115, v3, v115
	v_fma_f32 v115, v147, v115, v163
	v_cvt_pk_bf16_f32 v180, v112, v113
	v_cvt_pk_bf16_f32 v181, v114, v115
	global_store_dwordx2 v196, v[180:181], s[10:11]
	s_nop 0
	v_mul_f32_e32 v116, v116, v209
	v_mul_f32_e32 v116, v4, v116
	v_fma_f32 v116, v148, v116, v164
	v_mul_f32_e32 v117, v117, v209
	v_mul_f32_e32 v117, v5, v117
	v_fma_f32 v117, v149, v117, v165
	v_mul_f32_e32 v118, v118, v209
	v_mul_f32_e32 v118, v6, v118
	v_fma_f32 v118, v150, v118, v166
	v_mul_f32_e32 v119, v119, v209
	v_mul_f32_e32 v119, v7, v119
	v_fma_f32 v119, v151, v119, v167
	v_cvt_pk_bf16_f32 v180, v116, v117
	v_cvt_pk_bf16_f32 v181, v118, v119
	global_store_dwordx2 v196, v[180:181], s[10:11] offset:512
	s_nop 0
	v_mul_f32_e32 v120, v120, v209
	v_mul_f32_e32 v120, v8, v120
	v_fma_f32 v120, v152, v120, v168
	v_mul_f32_e32 v121, v121, v209
	v_mul_f32_e32 v121, v9, v121
	v_fma_f32 v121, v153, v121, v169
	v_mul_f32_e32 v122, v122, v209
	v_mul_f32_e32 v122, v10, v122
	v_fma_f32 v122, v154, v122, v170
	v_mul_f32_e32 v123, v123, v209
	v_mul_f32_e32 v123, v11, v123
	v_fma_f32 v123, v155, v123, v171
	v_cvt_pk_bf16_f32 v180, v120, v121
	v_cvt_pk_bf16_f32 v181, v122, v123
	global_store_dwordx2 v196, v[180:181], s[10:11] offset:1024
	s_nop 0
	v_mul_f32_e32 v124, v124, v209
	v_mul_f32_e32 v124, v12, v124
	v_fma_f32 v124, v156, v124, v172
	v_mul_f32_e32 v125, v125, v209
	v_mul_f32_e32 v125, v13, v125
	v_fma_f32 v125, v157, v125, v173
	v_mul_f32_e32 v126, v126, v209
	v_mul_f32_e32 v126, v14, v126
	v_fma_f32 v126, v158, v126, v174
	v_mul_f32_e32 v127, v127, v209
	v_mul_f32_e32 v127, v15, v127
	v_fma_f32 v127, v159, v127, v175
	v_cvt_pk_bf16_f32 v180, v124, v125
	v_cvt_pk_bf16_f32 v181, v126, v127
	global_store_dwordx2 v196, v[180:181], s[10:11] offset:1536
	s_nop 0
	v_mul_f32_e32 v128, v128, v210
	v_mul_f32_e32 v128, v0, v128
	v_fma_f32 v128, v144, v128, v160
	v_mul_f32_e32 v129, v129, v210
	v_mul_f32_e32 v129, v1, v129
	v_fma_f32 v129, v145, v129, v161
	v_mul_f32_e32 v130, v130, v210
	v_mul_f32_e32 v130, v2, v130
	v_fma_f32 v130, v146, v130, v162
	v_mul_f32_e32 v131, v131, v210
	v_mul_f32_e32 v131, v3, v131
	v_fma_f32 v131, v147, v131, v163
	v_cvt_pk_bf16_f32 v180, v128, v129
	v_cvt_pk_bf16_f32 v181, v130, v131
	global_store_dwordx2 v196, v[180:181], s[10:11] offset:2048
	s_nop 0
	v_mul_f32_e32 v132, v132, v210
	v_mul_f32_e32 v132, v4, v132
	v_fma_f32 v132, v148, v132, v164
	v_mul_f32_e32 v133, v133, v210
	v_mul_f32_e32 v133, v5, v133
	v_fma_f32 v133, v149, v133, v165
	v_mul_f32_e32 v134, v134, v210
	v_mul_f32_e32 v134, v6, v134
	v_fma_f32 v134, v150, v134, v166
	v_mul_f32_e32 v135, v135, v210
	v_mul_f32_e32 v135, v7, v135
	v_fma_f32 v135, v151, v135, v167
	v_cvt_pk_bf16_f32 v180, v132, v133
	v_cvt_pk_bf16_f32 v181, v134, v135
	global_store_dwordx2 v196, v[180:181], s[10:11] offset:2560
	s_nop 0
	v_mul_f32_e32 v136, v136, v210
	v_mul_f32_e32 v136, v8, v136
	v_fma_f32 v136, v152, v136, v168
	v_mul_f32_e32 v137, v137, v210
	v_mul_f32_e32 v137, v9, v137
	v_fma_f32 v137, v153, v137, v169
	v_mul_f32_e32 v138, v138, v210
	v_mul_f32_e32 v138, v10, v138
	v_fma_f32 v138, v154, v138, v170
	v_mul_f32_e32 v139, v139, v210
	v_mul_f32_e32 v139, v11, v139
	v_fma_f32 v139, v155, v139, v171
	v_cvt_pk_bf16_f32 v180, v136, v137
	v_cvt_pk_bf16_f32 v181, v138, v139
	global_store_dwordx2 v196, v[180:181], s[10:11] offset:3072
	s_nop 0
	v_mul_f32_e32 v140, v140, v210
	v_mul_f32_e32 v140, v12, v140
	v_fma_f32 v140, v156, v140, v172
	v_mul_f32_e32 v141, v141, v210
	v_mul_f32_e32 v141, v13, v141
	v_fma_f32 v141, v157, v141, v173
	v_mul_f32_e32 v142, v142, v210
	v_mul_f32_e32 v142, v14, v142
	v_fma_f32 v142, v158, v142, v174
	v_mul_f32_e32 v143, v143, v210
	v_mul_f32_e32 v143, v15, v143
	v_fma_f32 v143, v159, v143, v175
	v_cvt_pk_bf16_f32 v180, v140, v141
	v_cvt_pk_bf16_f32 v181, v142, v143
	global_store_dwordx2 v196, v[180:181], s[10:11] offset:3584
	s_nop 0
	s_add_u32 s14, s14, 0x2000
	s_addc_u32 s15, s15, 0
	global_load_dwordx4 v[112:115], v194, s[14:15]
	global_load_dwordx4 v[116:119], v194, s[14:15] offset:1024
	global_load_dwordx4 v[120:123], v194, s[14:15] offset:2048
	global_load_dwordx4 v[124:127], v194, s[14:15] offset:3072
	global_load_dwordx4 v[128:131], v195, s[14:15]
	global_load_dwordx4 v[132:135], v195, s[14:15] offset:1024
	global_load_dwordx4 v[136:139], v195, s[14:15] offset:2048
	global_load_dwordx4 v[140:143], v195, s[14:15] offset:3072
	s_waitcnt vmcnt(48)
	v_pk_mul_f32 v[178:179], v[16:17], v[16:17]
	v_pk_fma_f32 v[178:179], v[18:19], v[18:19], v[178:179]
	v_pk_fma_f32 v[178:179], v[20:21], v[20:21], v[178:179]
	v_pk_fma_f32 v[178:179], v[22:23], v[22:23], v[178:179]
	v_pk_fma_f32 v[178:179], v[24:25], v[24:25], v[178:179]
	v_pk_fma_f32 v[178:179], v[26:27], v[26:27], v[178:179]
	v_pk_fma_f32 v[178:179], v[28:29], v[28:29], v[178:179]
	v_pk_fma_f32 v[178:179], v[30:31], v[30:31], v[178:179]
	v_pk_mul_f32 v[180:181], v[32:33], v[32:33]
	v_pk_fma_f32 v[180:181], v[34:35], v[34:35], v[180:181]
	v_pk_fma_f32 v[180:181], v[36:37], v[36:37], v[180:181]
	v_pk_fma_f32 v[180:181], v[38:39], v[38:39], v[180:181]
	v_pk_fma_f32 v[180:181], v[40:41], v[40:41], v[180:181]
	v_pk_fma_f32 v[180:181], v[42:43], v[42:43], v[180:181]
	v_pk_fma_f32 v[180:181], v[44:45], v[44:45], v[180:181]
	v_pk_fma_f32 v[180:181], v[46:47], v[46:47], v[180:181]
	v_add_f32_e32 v176, v178, v179
	v_add_f32_e32 v177, v180, v181
	ds_bpermute_b32 v178, v198, v176
	ds_bpermute_b32 v179, v198, v177
	s_waitcnt lgkmcnt(0)
	v_add_f32_e32 v176, v176, v178
	v_add_f32_e32 v177, v177, v179
	ds_bpermute_b32 v178, v199, v176
	ds_bpermute_b32 v179, v199, v177
	s_waitcnt lgkmcnt(0)
	v_add_f32_e32 v176, v176, v178
	v_add_f32_e32 v177, v177, v179
	ds_bpermute_b32 v178, v200, v176
	ds_bpermute_b32 v179, v200, v177
	s_waitcnt lgkmcnt(0)
	v_add_f32_e32 v176, v176, v178
	v_add_f32_e32 v177, v177, v179
	ds_bpermute_b32 v178, v201, v176
	ds_bpermute_b32 v179, v201, v177
	s_waitcnt lgkmcnt(0)
	v_add_f32_e32 v176, v176, v178
	v_add_f32_e32 v177, v177, v179
	ds_bpermute_b32 v178, v202, v176
	ds_bpermute_b32 v179, v202, v177
	s_waitcnt lgkmcnt(0)
	v_add_f32_e32 v176, v176, v178
	v_add_f32_e32 v177, v177, v179
	ds_bpermute_b32 v178, v203, v176
	ds_bpermute_b32 v179, v203, v177
	s_waitcnt lgkmcnt(0)
	v_add_f32_e32 v176, v176, v178
	v_add_f32_e32 v177, v177, v179
	v_fmamk_f32 v176, v176, 0x3a800000, v208
	v_mul_f32_e32 v178, 0x4b800000, v176
	v_cmp_gt_f32_e32 vcc, s27, v176
	s_nop 1
	v_cndmask_b32_e32 v176, v176, v178, vcc
	v_rsq_f32_e32 v209, v176
	s_nop 0
	v_mul_f32_e32 v178, 0x45800000, v209
	v_cndmask_b32_e32 v209, v209, v178, vcc
	v_fmamk_f32 v177, v177, 0x3a800000, v208
	v_mul_f32_e32 v178, 0x4b800000, v177
	v_cmp_gt_f32_e32 vcc, s27, v177
	s_nop 1
	v_cndmask_b32_e32 v177, v177, v178, vcc
	v_rsq_f32_e32 v210, v177
	s_nop 0
	v_mul_f32_e32 v178, 0x45800000, v210
	v_cndmask_b32_e32 v210, v210, v178, vcc
	s_add_u32 s10, s10, 0x1000
	s_addc_u32 s11, s11, 0
	v_mul_f32_e32 v16, v16, v209
	v_mul_f32_e32 v16, v0, v16
	v_fma_f32 v16, v144, v16, v160
	v_mul_f32_e32 v17, v17, v209
	v_mul_f32_e32 v17, v1, v17
	v_fma_f32 v17, v145, v17, v161
	v_mul_f32_e32 v18, v18, v209
	v_mul_f32_e32 v18, v2, v18
	v_fma_f32 v18, v146, v18, v162
	v_mul_f32_e32 v19, v19, v209
	v_mul_f32_e32 v19, v3, v19
	v_fma_f32 v19, v147, v19, v163
	v_cvt_pk_bf16_f32 v180, v16, v17
	v_cvt_pk_bf16_f32 v181, v18, v19
	global_store_dwordx2 v196, v[180:181], s[10:11]
	s_nop 0
	v_mul_f32_e32 v20, v20, v209
	v_mul_f32_e32 v20, v4, v20
	v_fma_f32 v20, v148, v20, v164
	v_mul_f32_e32 v21, v21, v209
	v_mul_f32_e32 v21, v5, v21
	v_fma_f32 v21, v149, v21, v165
	v_mul_f32_e32 v22, v22, v209
	v_mul_f32_e32 v22, v6, v22
	v_fma_f32 v22, v150, v22, v166
	v_mul_f32_e32 v23, v23, v209
	v_mul_f32_e32 v23, v7, v23
	v_fma_f32 v23, v151, v23, v167
	v_cvt_pk_bf16_f32 v180, v20, v21
	v_cvt_pk_bf16_f32 v181, v22, v23
	global_store_dwordx2 v196, v[180:181], s[10:11] offset:512
	s_nop 0
	v_mul_f32_e32 v24, v24, v209
	v_mul_f32_e32 v24, v8, v24
	v_fma_f32 v24, v152, v24, v168
	v_mul_f32_e32 v25, v25, v209
	v_mul_f32_e32 v25, v9, v25
	v_fma_f32 v25, v153, v25, v169
	v_mul_f32_e32 v26, v26, v209
	v_mul_f32_e32 v26, v10, v26
	v_fma_f32 v26, v154, v26, v170
	v_mul_f32_e32 v27, v27, v209
	v_mul_f32_e32 v27, v11, v27
	v_fma_f32 v27, v155, v27, v171
	v_cvt_pk_bf16_f32 v180, v24, v25
	v_cvt_pk_bf16_f32 v181, v26, v27
	global_store_dwordx2 v196, v[180:181], s[10:11] offset:1024
	s_nop 0
	v_mul_f32_e32 v28, v28, v209
	v_mul_f32_e32 v28, v12, v28
	v_fma_f32 v28, v156, v28, v172
	v_mul_f32_e32 v29, v29, v209
	v_mul_f32_e32 v29, v13, v29
	v_fma_f32 v29, v157, v29, v173
	v_mul_f32_e32 v30, v30, v209
	v_mul_f32_e32 v30, v14, v30
	v_fma_f32 v30, v158, v30, v174
	v_mul_f32_e32 v31, v31, v209
	v_mul_f32_e32 v31, v15, v31
	v_fma_f32 v31, v159, v31, v175
	v_cvt_pk_bf16_f32 v180, v28, v29
	v_cvt_pk_bf16_f32 v181, v30, v31
	global_store_dwordx2 v196, v[180:181], s[10:11] offset:1536
	s_nop 0
	v_mul_f32_e32 v32, v32, v210
	v_mul_f32_e32 v32, v0, v32
	v_fma_f32 v32, v144, v32, v160
	v_mul_f32_e32 v33, v33, v210
	v_mul_f32_e32 v33, v1, v33
	v_fma_f32 v33, v145, v33, v161
	v_mul_f32_e32 v34, v34, v210
	v_mul_f32_e32 v34, v2, v34
	v_fma_f32 v34, v146, v34, v162
	v_mul_f32_e32 v35, v35, v210
	v_mul_f32_e32 v35, v3, v35
	v_fma_f32 v35, v147, v35, v163
	v_cvt_pk_bf16_f32 v180, v32, v33
	v_cvt_pk_bf16_f32 v181, v34, v35
	global_store_dwordx2 v196, v[180:181], s[10:11] offset:2048
	s_nop 0
	v_mul_f32_e32 v36, v36, v210
	v_mul_f32_e32 v36, v4, v36
	v_fma_f32 v36, v148, v36, v164
	v_mul_f32_e32 v37, v37, v210
	v_mul_f32_e32 v37, v5, v37
	v_fma_f32 v37, v149, v37, v165
	v_mul_f32_e32 v38, v38, v210
	v_mul_f32_e32 v38, v6, v38
	v_fma_f32 v38, v150, v38, v166
	v_mul_f32_e32 v39, v39, v210
	v_mul_f32_e32 v39, v7, v39
	v_fma_f32 v39, v151, v39, v167
	v_cvt_pk_bf16_f32 v180, v36, v37
	v_cvt_pk_bf16_f32 v181, v38, v39
	global_store_dwordx2 v196, v[180:181], s[10:11] offset:2560
	s_nop 0
	v_mul_f32_e32 v40, v40, v210
	v_mul_f32_e32 v40, v8, v40
	v_fma_f32 v40, v152, v40, v168
	v_mul_f32_e32 v41, v41, v210
	v_mul_f32_e32 v41, v9, v41
	v_fma_f32 v41, v153, v41, v169
	v_mul_f32_e32 v42, v42, v210
	v_mul_f32_e32 v42, v10, v42
	v_fma_f32 v42, v154, v42, v170
	v_mul_f32_e32 v43, v43, v210
	v_mul_f32_e32 v43, v11, v43
	v_fma_f32 v43, v155, v43, v171
	v_cvt_pk_bf16_f32 v180, v40, v41
	v_cvt_pk_bf16_f32 v181, v42, v43
	global_store_dwordx2 v196, v[180:181], s[10:11] offset:3072
	s_nop 0
	v_mul_f32_e32 v44, v44, v210
	v_mul_f32_e32 v44, v12, v44
	v_fma_f32 v44, v156, v44, v172
	v_mul_f32_e32 v45, v45, v210
	v_mul_f32_e32 v45, v13, v45
	v_fma_f32 v45, v157, v45, v173
	v_mul_f32_e32 v46, v46, v210
	v_mul_f32_e32 v46, v14, v46
	v_fma_f32 v46, v158, v46, v174
	v_mul_f32_e32 v47, v47, v210
	v_mul_f32_e32 v47, v15, v47
	v_fma_f32 v47, v159, v47, v175
	v_cvt_pk_bf16_f32 v180, v44, v45
	v_cvt_pk_bf16_f32 v181, v46, v47
	global_store_dwordx2 v196, v[180:181], s[10:11] offset:3584
	s_nop 0
	s_waitcnt vmcnt(40)
	v_pk_mul_f32 v[178:179], v[48:49], v[48:49]
	v_pk_fma_f32 v[178:179], v[50:51], v[50:51], v[178:179]
	v_pk_fma_f32 v[178:179], v[52:53], v[52:53], v[178:179]
	v_pk_fma_f32 v[178:179], v[54:55], v[54:55], v[178:179]
	v_pk_fma_f32 v[178:179], v[56:57], v[56:57], v[178:179]
	v_pk_fma_f32 v[178:179], v[58:59], v[58:59], v[178:179]
	v_pk_fma_f32 v[178:179], v[60:61], v[60:61], v[178:179]
	v_pk_fma_f32 v[178:179], v[62:63], v[62:63], v[178:179]
	v_pk_mul_f32 v[180:181], v[64:65], v[64:65]
	v_pk_fma_f32 v[180:181], v[66:67], v[66:67], v[180:181]
	v_pk_fma_f32 v[180:181], v[68:69], v[68:69], v[180:181]
	v_pk_fma_f32 v[180:181], v[70:71], v[70:71], v[180:181]
	v_pk_fma_f32 v[180:181], v[72:73], v[72:73], v[180:181]
	v_pk_fma_f32 v[180:181], v[74:75], v[74:75], v[180:181]
	v_pk_fma_f32 v[180:181], v[76:77], v[76:77], v[180:181]
	v_pk_fma_f32 v[180:181], v[78:79], v[78:79], v[180:181]
	v_add_f32_e32 v176, v178, v179
	v_add_f32_e32 v177, v180, v181
	ds_bpermute_b32 v178, v198, v176
	ds_bpermute_b32 v179, v198, v177
	s_waitcnt lgkmcnt(0)
	v_add_f32_e32 v176, v176, v178
	v_add_f32_e32 v177, v177, v179
	ds_bpermute_b32 v178, v199, v176
	ds_bpermute_b32 v179, v199, v177
	s_waitcnt lgkmcnt(0)
	v_add_f32_e32 v176, v176, v178
	v_add_f32_e32 v177, v177, v179
	ds_bpermute_b32 v178, v200, v176
	ds_bpermute_b32 v179, v200, v177
	s_waitcnt lgkmcnt(0)
	v_add_f32_e32 v176, v176, v178
	v_add_f32_e32 v177, v177, v179
	ds_bpermute_b32 v178, v201, v176
	ds_bpermute_b32 v179, v201, v177
	s_waitcnt lgkmcnt(0)
	v_add_f32_e32 v176, v176, v178
	v_add_f32_e32 v177, v177, v179
	ds_bpermute_b32 v178, v202, v176
	ds_bpermute_b32 v179, v202, v177
	s_waitcnt lgkmcnt(0)
	v_add_f32_e32 v176, v176, v178
	v_add_f32_e32 v177, v177, v179
	ds_bpermute_b32 v178, v203, v176
	ds_bpermute_b32 v179, v203, v177
	s_waitcnt lgkmcnt(0)
	v_add_f32_e32 v176, v176, v178
	v_add_f32_e32 v177, v177, v179
	v_fmamk_f32 v176, v176, 0x3a800000, v208
	v_mul_f32_e32 v178, 0x4b800000, v176
	v_cmp_gt_f32_e32 vcc, s27, v176
	s_nop 1
	v_cndmask_b32_e32 v176, v176, v178, vcc
	v_rsq_f32_e32 v209, v176
	s_nop 0
	v_mul_f32_e32 v178, 0x45800000, v209
	v_cndmask_b32_e32 v209, v209, v178, vcc
	v_fmamk_f32 v177, v177, 0x3a800000, v208
	v_mul_f32_e32 v178, 0x4b800000, v177
	v_cmp_gt_f32_e32 vcc, s27, v177
	s_nop 1
	v_cndmask_b32_e32 v177, v177, v178, vcc
	v_rsq_f32_e32 v210, v177
	s_nop 0
	v_mul_f32_e32 v178, 0x45800000, v210
	v_cndmask_b32_e32 v210, v210, v178, vcc
	s_add_u32 s10, s10, 0x1000
	s_addc_u32 s11, s11, 0
	v_mul_f32_e32 v48, v48, v209
	v_mul_f32_e32 v48, v0, v48
	v_fma_f32 v48, v144, v48, v160
	v_mul_f32_e32 v49, v49, v209
	v_mul_f32_e32 v49, v1, v49
	v_fma_f32 v49, v145, v49, v161
	v_mul_f32_e32 v50, v50, v209
	v_mul_f32_e32 v50, v2, v50
	v_fma_f32 v50, v146, v50, v162
	v_mul_f32_e32 v51, v51, v209
	v_mul_f32_e32 v51, v3, v51
	v_fma_f32 v51, v147, v51, v163
	v_cvt_pk_bf16_f32 v180, v48, v49
	v_cvt_pk_bf16_f32 v181, v50, v51
	global_store_dwordx2 v196, v[180:181], s[10:11]
	s_nop 0
	v_mul_f32_e32 v52, v52, v209
	v_mul_f32_e32 v52, v4, v52
	v_fma_f32 v52, v148, v52, v164
	v_mul_f32_e32 v53, v53, v209
	v_mul_f32_e32 v53, v5, v53
	v_fma_f32 v53, v149, v53, v165
	v_mul_f32_e32 v54, v54, v209
	v_mul_f32_e32 v54, v6, v54
	v_fma_f32 v54, v150, v54, v166
	v_mul_f32_e32 v55, v55, v209
	v_mul_f32_e32 v55, v7, v55
	v_fma_f32 v55, v151, v55, v167
	v_cvt_pk_bf16_f32 v180, v52, v53
	v_cvt_pk_bf16_f32 v181, v54, v55
	global_store_dwordx2 v196, v[180:181], s[10:11] offset:512
	s_nop 0
	v_mul_f32_e32 v56, v56, v209
	v_mul_f32_e32 v56, v8, v56
	v_fma_f32 v56, v152, v56, v168
	v_mul_f32_e32 v57, v57, v209
	v_mul_f32_e32 v57, v9, v57
	v_fma_f32 v57, v153, v57, v169
	v_mul_f32_e32 v58, v58, v209
	v_mul_f32_e32 v58, v10, v58
	v_fma_f32 v58, v154, v58, v170
	v_mul_f32_e32 v59, v59, v209
	v_mul_f32_e32 v59, v11, v59
	v_fma_f32 v59, v155, v59, v171
	v_cvt_pk_bf16_f32 v180, v56, v57
	v_cvt_pk_bf16_f32 v181, v58, v59
	global_store_dwordx2 v196, v[180:181], s[10:11] offset:1024
	s_nop 0
	v_mul_f32_e32 v60, v60, v209
	v_mul_f32_e32 v60, v12, v60
	v_fma_f32 v60, v156, v60, v172
	v_mul_f32_e32 v61, v61, v209
	v_mul_f32_e32 v61, v13, v61
	v_fma_f32 v61, v157, v61, v173
	v_mul_f32_e32 v62, v62, v209
	v_mul_f32_e32 v62, v14, v62
	v_fma_f32 v62, v158, v62, v174
	v_mul_f32_e32 v63, v63, v209
	v_mul_f32_e32 v63, v15, v63
	v_fma_f32 v63, v159, v63, v175
	v_cvt_pk_bf16_f32 v180, v60, v61
	v_cvt_pk_bf16_f32 v181, v62, v63
	global_store_dwordx2 v196, v[180:181], s[10:11] offset:1536
	s_nop 0
	v_mul_f32_e32 v64, v64, v210
	v_mul_f32_e32 v64, v0, v64
	v_fma_f32 v64, v144, v64, v160
	v_mul_f32_e32 v65, v65, v210
	v_mul_f32_e32 v65, v1, v65
	v_fma_f32 v65, v145, v65, v161
	v_mul_f32_e32 v66, v66, v210
	v_mul_f32_e32 v66, v2, v66
	v_fma_f32 v66, v146, v66, v162
	v_mul_f32_e32 v67, v67, v210
	v_mul_f32_e32 v67, v3, v67
	v_fma_f32 v67, v147, v67, v163
	v_cvt_pk_bf16_f32 v180, v64, v65
	v_cvt_pk_bf16_f32 v181, v66, v67
	global_store_dwordx2 v196, v[180:181], s[10:11] offset:2048
	s_nop 0
	v_mul_f32_e32 v68, v68, v210
	v_mul_f32_e32 v68, v4, v68
	v_fma_f32 v68, v148, v68, v164
	v_mul_f32_e32 v69, v69, v210
	v_mul_f32_e32 v69, v5, v69
	v_fma_f32 v69, v149, v69, v165
	v_mul_f32_e32 v70, v70, v210
	v_mul_f32_e32 v70, v6, v70
	v_fma_f32 v70, v150, v70, v166
	v_mul_f32_e32 v71, v71, v210
	v_mul_f32_e32 v71, v7, v71
	v_fma_f32 v71, v151, v71, v167
	v_cvt_pk_bf16_f32 v180, v68, v69
	v_cvt_pk_bf16_f32 v181, v70, v71
	global_store_dwordx2 v196, v[180:181], s[10:11] offset:2560
	s_nop 0
	v_mul_f32_e32 v72, v72, v210
	v_mul_f32_e32 v72, v8, v72
	v_fma_f32 v72, v152, v72, v168
	v_mul_f32_e32 v73, v73, v210
	v_mul_f32_e32 v73, v9, v73
	v_fma_f32 v73, v153, v73, v169
	v_mul_f32_e32 v74, v74, v210
	v_mul_f32_e32 v74, v10, v74
	v_fma_f32 v74, v154, v74, v170
	v_mul_f32_e32 v75, v75, v210
	v_mul_f32_e32 v75, v11, v75
	v_fma_f32 v75, v155, v75, v171
	v_cvt_pk_bf16_f32 v180, v72, v73
	v_cvt_pk_bf16_f32 v181, v74, v75
	global_store_dwordx2 v196, v[180:181], s[10:11] offset:3072
	s_nop 0
	v_mul_f32_e32 v76, v76, v210
	v_mul_f32_e32 v76, v12, v76
	v_fma_f32 v76, v156, v76, v172
	v_mul_f32_e32 v77, v77, v210
	v_mul_f32_e32 v77, v13, v77
	v_fma_f32 v77, v157, v77, v173
	v_mul_f32_e32 v78, v78, v210
	v_mul_f32_e32 v78, v14, v78
	v_fma_f32 v78, v158, v78, v174
	v_mul_f32_e32 v79, v79, v210
	v_mul_f32_e32 v79, v15, v79
	v_fma_f32 v79, v159, v79, v175
	v_cvt_pk_bf16_f32 v180, v76, v77
	v_cvt_pk_bf16_f32 v181, v78, v79
	global_store_dwordx2 v196, v[180:181], s[10:11] offset:3584
	s_nop 0
	s_waitcnt vmcnt(32)
	v_pk_mul_f32 v[178:179], v[80:81], v[80:81]
	v_pk_fma_f32 v[178:179], v[82:83], v[82:83], v[178:179]
	v_pk_fma_f32 v[178:179], v[84:85], v[84:85], v[178:179]
	v_pk_fma_f32 v[178:179], v[86:87], v[86:87], v[178:179]
	v_pk_fma_f32 v[178:179], v[88:89], v[88:89], v[178:179]
	v_pk_fma_f32 v[178:179], v[90:91], v[90:91], v[178:179]
	v_pk_fma_f32 v[178:179], v[92:93], v[92:93], v[178:179]
	v_pk_fma_f32 v[178:179], v[94:95], v[94:95], v[178:179]
	v_pk_mul_f32 v[180:181], v[96:97], v[96:97]
	v_pk_fma_f32 v[180:181], v[98:99], v[98:99], v[180:181]
	v_pk_fma_f32 v[180:181], v[100:101], v[100:101], v[180:181]
	v_pk_fma_f32 v[180:181], v[102:103], v[102:103], v[180:181]
	v_pk_fma_f32 v[180:181], v[104:105], v[104:105], v[180:181]
	v_pk_fma_f32 v[180:181], v[106:107], v[106:107], v[180:181]
	v_pk_fma_f32 v[180:181], v[108:109], v[108:109], v[180:181]
	v_pk_fma_f32 v[180:181], v[110:111], v[110:111], v[180:181]
	v_add_f32_e32 v176, v178, v179
	v_add_f32_e32 v177, v180, v181
	ds_bpermute_b32 v178, v198, v176
	ds_bpermute_b32 v179, v198, v177
	s_waitcnt lgkmcnt(0)
	v_add_f32_e32 v176, v176, v178
	v_add_f32_e32 v177, v177, v179
	ds_bpermute_b32 v178, v199, v176
	ds_bpermute_b32 v179, v199, v177
	s_waitcnt lgkmcnt(0)
	v_add_f32_e32 v176, v176, v178
	v_add_f32_e32 v177, v177, v179
	ds_bpermute_b32 v178, v200, v176
	ds_bpermute_b32 v179, v200, v177
	s_waitcnt lgkmcnt(0)
	v_add_f32_e32 v176, v176, v178
	v_add_f32_e32 v177, v177, v179
	ds_bpermute_b32 v178, v201, v176
	ds_bpermute_b32 v179, v201, v177
	s_waitcnt lgkmcnt(0)
	v_add_f32_e32 v176, v176, v178
	v_add_f32_e32 v177, v177, v179
	ds_bpermute_b32 v178, v202, v176
	ds_bpermute_b32 v179, v202, v177
	s_waitcnt lgkmcnt(0)
	v_add_f32_e32 v176, v176, v178
	v_add_f32_e32 v177, v177, v179
	ds_bpermute_b32 v178, v203, v176
	ds_bpermute_b32 v179, v203, v177
	s_waitcnt lgkmcnt(0)
	v_add_f32_e32 v176, v176, v178
	v_add_f32_e32 v177, v177, v179
	v_fmamk_f32 v176, v176, 0x3a800000, v208
	v_mul_f32_e32 v178, 0x4b800000, v176
	v_cmp_gt_f32_e32 vcc, s27, v176
	s_nop 1
	v_cndmask_b32_e32 v176, v176, v178, vcc
	v_rsq_f32_e32 v209, v176
	s_nop 0
	v_mul_f32_e32 v178, 0x45800000, v209
	v_cndmask_b32_e32 v209, v209, v178, vcc
	v_fmamk_f32 v177, v177, 0x3a800000, v208
	v_mul_f32_e32 v178, 0x4b800000, v177
	v_cmp_gt_f32_e32 vcc, s27, v177
	s_nop 1
	v_cndmask_b32_e32 v177, v177, v178, vcc
	v_rsq_f32_e32 v210, v177
	s_nop 0
	v_mul_f32_e32 v178, 0x45800000, v210
	v_cndmask_b32_e32 v210, v210, v178, vcc
	s_add_u32 s10, s10, 0x1000
	s_addc_u32 s11, s11, 0
	v_mul_f32_e32 v80, v80, v209
	v_mul_f32_e32 v80, v0, v80
	v_fma_f32 v80, v144, v80, v160
	v_mul_f32_e32 v81, v81, v209
	v_mul_f32_e32 v81, v1, v81
	v_fma_f32 v81, v145, v81, v161
	v_mul_f32_e32 v82, v82, v209
	v_mul_f32_e32 v82, v2, v82
	v_fma_f32 v82, v146, v82, v162
	v_mul_f32_e32 v83, v83, v209
	v_mul_f32_e32 v83, v3, v83
	v_fma_f32 v83, v147, v83, v163
	v_cvt_pk_bf16_f32 v180, v80, v81
	v_cvt_pk_bf16_f32 v181, v82, v83
	global_store_dwordx2 v196, v[180:181], s[10:11]
	s_nop 0
	v_mul_f32_e32 v84, v84, v209
	v_mul_f32_e32 v84, v4, v84
	v_fma_f32 v84, v148, v84, v164
	v_mul_f32_e32 v85, v85, v209
	v_mul_f32_e32 v85, v5, v85
	v_fma_f32 v85, v149, v85, v165
	v_mul_f32_e32 v86, v86, v209
	v_mul_f32_e32 v86, v6, v86
	v_fma_f32 v86, v150, v86, v166
	v_mul_f32_e32 v87, v87, v209
	v_mul_f32_e32 v87, v7, v87
	v_fma_f32 v87, v151, v87, v167
	v_cvt_pk_bf16_f32 v180, v84, v85
	v_cvt_pk_bf16_f32 v181, v86, v87
	global_store_dwordx2 v196, v[180:181], s[10:11] offset:512
	s_nop 0
	v_mul_f32_e32 v88, v88, v209
	v_mul_f32_e32 v88, v8, v88
	v_fma_f32 v88, v152, v88, v168
	v_mul_f32_e32 v89, v89, v209
	v_mul_f32_e32 v89, v9, v89
	v_fma_f32 v89, v153, v89, v169
	v_mul_f32_e32 v90, v90, v209
	v_mul_f32_e32 v90, v10, v90
	v_fma_f32 v90, v154, v90, v170
	v_mul_f32_e32 v91, v91, v209
	v_mul_f32_e32 v91, v11, v91
	v_fma_f32 v91, v155, v91, v171
	v_cvt_pk_bf16_f32 v180, v88, v89
	v_cvt_pk_bf16_f32 v181, v90, v91
	global_store_dwordx2 v196, v[180:181], s[10:11] offset:1024
	s_nop 0
	v_mul_f32_e32 v92, v92, v209
	v_mul_f32_e32 v92, v12, v92
	v_fma_f32 v92, v156, v92, v172
	v_mul_f32_e32 v93, v93, v209
	v_mul_f32_e32 v93, v13, v93
	v_fma_f32 v93, v157, v93, v173
	v_mul_f32_e32 v94, v94, v209
	v_mul_f32_e32 v94, v14, v94
	v_fma_f32 v94, v158, v94, v174
	v_mul_f32_e32 v95, v95, v209
	v_mul_f32_e32 v95, v15, v95
	v_fma_f32 v95, v159, v95, v175
	v_cvt_pk_bf16_f32 v180, v92, v93
	v_cvt_pk_bf16_f32 v181, v94, v95
	global_store_dwordx2 v196, v[180:181], s[10:11] offset:1536
	s_nop 0
	v_mul_f32_e32 v96, v96, v210
	v_mul_f32_e32 v96, v0, v96
	v_fma_f32 v96, v144, v96, v160
	v_mul_f32_e32 v97, v97, v210
	v_mul_f32_e32 v97, v1, v97
	v_fma_f32 v97, v145, v97, v161
	v_mul_f32_e32 v98, v98, v210
	v_mul_f32_e32 v98, v2, v98
	v_fma_f32 v98, v146, v98, v162
	v_mul_f32_e32 v99, v99, v210
	v_mul_f32_e32 v99, v3, v99
	v_fma_f32 v99, v147, v99, v163
	v_cvt_pk_bf16_f32 v180, v96, v97
	v_cvt_pk_bf16_f32 v181, v98, v99
	global_store_dwordx2 v196, v[180:181], s[10:11] offset:2048
	s_nop 0
	v_mul_f32_e32 v100, v100, v210
	v_mul_f32_e32 v100, v4, v100
	v_fma_f32 v100, v148, v100, v164
	v_mul_f32_e32 v101, v101, v210
	v_mul_f32_e32 v101, v5, v101
	v_fma_f32 v101, v149, v101, v165
	v_mul_f32_e32 v102, v102, v210
	v_mul_f32_e32 v102, v6, v102
	v_fma_f32 v102, v150, v102, v166
	v_mul_f32_e32 v103, v103, v210
	v_mul_f32_e32 v103, v7, v103
	v_fma_f32 v103, v151, v103, v167
	v_cvt_pk_bf16_f32 v180, v100, v101
	v_cvt_pk_bf16_f32 v181, v102, v103
	global_store_dwordx2 v196, v[180:181], s[10:11] offset:2560
	s_nop 0
	v_mul_f32_e32 v104, v104, v210
	v_mul_f32_e32 v104, v8, v104
	v_fma_f32 v104, v152, v104, v168
	v_mul_f32_e32 v105, v105, v210
	v_mul_f32_e32 v105, v9, v105
	v_fma_f32 v105, v153, v105, v169
	v_mul_f32_e32 v106, v106, v210
	v_mul_f32_e32 v106, v10, v106
	v_fma_f32 v106, v154, v106, v170
	v_mul_f32_e32 v107, v107, v210
	v_mul_f32_e32 v107, v11, v107
	v_fma_f32 v107, v155, v107, v171
	v_cvt_pk_bf16_f32 v180, v104, v105
	v_cvt_pk_bf16_f32 v181, v106, v107
	global_store_dwordx2 v196, v[180:181], s[10:11] offset:3072
	s_nop 0
	v_mul_f32_e32 v108, v108, v210
	v_mul_f32_e32 v108, v12, v108
	v_fma_f32 v108, v156, v108, v172
	v_mul_f32_e32 v109, v109, v210
	v_mul_f32_e32 v109, v13, v109
	v_fma_f32 v109, v157, v109, v173
	v_mul_f32_e32 v110, v110, v210
	v_mul_f32_e32 v110, v14, v110
	v_fma_f32 v110, v158, v110, v174
	v_mul_f32_e32 v111, v111, v210
	v_mul_f32_e32 v111, v15, v111
	v_fma_f32 v111, v159, v111, v175
	v_cvt_pk_bf16_f32 v180, v108, v109
	v_cvt_pk_bf16_f32 v181, v110, v111
	global_store_dwordx2 v196, v[180:181], s[10:11] offset:3584
	s_nop 0
	s_waitcnt vmcnt(24)
	v_pk_mul_f32 v[178:179], v[112:113], v[112:113]
	v_pk_fma_f32 v[178:179], v[114:115], v[114:115], v[178:179]
	v_pk_fma_f32 v[178:179], v[116:117], v[116:117], v[178:179]
	v_pk_fma_f32 v[178:179], v[118:119], v[118:119], v[178:179]
	v_pk_fma_f32 v[178:179], v[120:121], v[120:121], v[178:179]
	v_pk_fma_f32 v[178:179], v[122:123], v[122:123], v[178:179]
	v_pk_fma_f32 v[178:179], v[124:125], v[124:125], v[178:179]
	v_pk_fma_f32 v[178:179], v[126:127], v[126:127], v[178:179]
	v_pk_mul_f32 v[180:181], v[128:129], v[128:129]
	v_pk_fma_f32 v[180:181], v[130:131], v[130:131], v[180:181]
	v_pk_fma_f32 v[180:181], v[132:133], v[132:133], v[180:181]
	v_pk_fma_f32 v[180:181], v[134:135], v[134:135], v[180:181]
	v_pk_fma_f32 v[180:181], v[136:137], v[136:137], v[180:181]
	v_pk_fma_f32 v[180:181], v[138:139], v[138:139], v[180:181]
	v_pk_fma_f32 v[180:181], v[140:141], v[140:141], v[180:181]
	v_pk_fma_f32 v[180:181], v[142:143], v[142:143], v[180:181]
	v_add_f32_e32 v176, v178, v179
	v_add_f32_e32 v177, v180, v181
	ds_bpermute_b32 v178, v198, v176
	ds_bpermute_b32 v179, v198, v177
	s_waitcnt lgkmcnt(0)
	v_add_f32_e32 v176, v176, v178
	v_add_f32_e32 v177, v177, v179
	ds_bpermute_b32 v178, v199, v176
	ds_bpermute_b32 v179, v199, v177
	s_waitcnt lgkmcnt(0)
	v_add_f32_e32 v176, v176, v178
	v_add_f32_e32 v177, v177, v179
	ds_bpermute_b32 v178, v200, v176
	ds_bpermute_b32 v179, v200, v177
	s_waitcnt lgkmcnt(0)
	v_add_f32_e32 v176, v176, v178
	v_add_f32_e32 v177, v177, v179
	ds_bpermute_b32 v178, v201, v176
	ds_bpermute_b32 v179, v201, v177
	s_waitcnt lgkmcnt(0)
	v_add_f32_e32 v176, v176, v178
	v_add_f32_e32 v177, v177, v179
	ds_bpermute_b32 v178, v202, v176
	ds_bpermute_b32 v179, v202, v177
	s_waitcnt lgkmcnt(0)
	v_add_f32_e32 v176, v176, v178
	v_add_f32_e32 v177, v177, v179
	ds_bpermute_b32 v178, v203, v176
	ds_bpermute_b32 v179, v203, v177
	s_waitcnt lgkmcnt(0)
	v_add_f32_e32 v176, v176, v178
	v_add_f32_e32 v177, v177, v179
	v_fmamk_f32 v176, v176, 0x3a800000, v208
	v_mul_f32_e32 v178, 0x4b800000, v176
	v_cmp_gt_f32_e32 vcc, s27, v176
	s_nop 1
	v_cndmask_b32_e32 v176, v176, v178, vcc
	v_rsq_f32_e32 v209, v176
	s_nop 0
	v_mul_f32_e32 v178, 0x45800000, v209
	v_cndmask_b32_e32 v209, v209, v178, vcc
	v_fmamk_f32 v177, v177, 0x3a800000, v208
	v_mul_f32_e32 v178, 0x4b800000, v177
	v_cmp_gt_f32_e32 vcc, s27, v177
	s_nop 1
	v_cndmask_b32_e32 v177, v177, v178, vcc
	v_rsq_f32_e32 v210, v177
	s_nop 0
	v_mul_f32_e32 v178, 0x45800000, v210
	v_cndmask_b32_e32 v210, v210, v178, vcc
	s_add_u32 s10, s10, 0x1000
	s_addc_u32 s11, s11, 0
	v_mul_f32_e32 v112, v112, v209
	v_mul_f32_e32 v112, v0, v112
	v_fma_f32 v112, v144, v112, v160
	v_mul_f32_e32 v113, v113, v209
	v_mul_f32_e32 v113, v1, v113
	v_fma_f32 v113, v145, v113, v161
	v_mul_f32_e32 v114, v114, v209
	v_mul_f32_e32 v114, v2, v114
	v_fma_f32 v114, v146, v114, v162
	v_mul_f32_e32 v115, v115, v209
	v_mul_f32_e32 v115, v3, v115
	v_fma_f32 v115, v147, v115, v163
	v_cvt_pk_bf16_f32 v180, v112, v113
	v_cvt_pk_bf16_f32 v181, v114, v115
	global_store_dwordx2 v196, v[180:181], s[10:11]
	s_nop 0
	v_mul_f32_e32 v116, v116, v209
	v_mul_f32_e32 v116, v4, v116
	v_fma_f32 v116, v148, v116, v164
	v_mul_f32_e32 v117, v117, v209
	v_mul_f32_e32 v117, v5, v117
	v_fma_f32 v117, v149, v117, v165
	v_mul_f32_e32 v118, v118, v209
	v_mul_f32_e32 v118, v6, v118
	v_fma_f32 v118, v150, v118, v166
	v_mul_f32_e32 v119, v119, v209
	v_mul_f32_e32 v119, v7, v119
	v_fma_f32 v119, v151, v119, v167
	v_cvt_pk_bf16_f32 v180, v116, v117
	v_cvt_pk_bf16_f32 v181, v118, v119
	global_store_dwordx2 v196, v[180:181], s[10:11] offset:512
	s_nop 0
	v_mul_f32_e32 v120, v120, v209
	v_mul_f32_e32 v120, v8, v120
	v_fma_f32 v120, v152, v120, v168
	v_mul_f32_e32 v121, v121, v209
	v_mul_f32_e32 v121, v9, v121
	v_fma_f32 v121, v153, v121, v169
	v_mul_f32_e32 v122, v122, v209
	v_mul_f32_e32 v122, v10, v122
	v_fma_f32 v122, v154, v122, v170
	v_mul_f32_e32 v123, v123, v209
	v_mul_f32_e32 v123, v11, v123
	v_fma_f32 v123, v155, v123, v171
	v_cvt_pk_bf16_f32 v180, v120, v121
	v_cvt_pk_bf16_f32 v181, v122, v123
	global_store_dwordx2 v196, v[180:181], s[10:11] offset:1024
	s_nop 0
	v_mul_f32_e32 v124, v124, v209
	v_mul_f32_e32 v124, v12, v124
	v_fma_f32 v124, v156, v124, v172
	v_mul_f32_e32 v125, v125, v209
	v_mul_f32_e32 v125, v13, v125
	v_fma_f32 v125, v157, v125, v173
	v_mul_f32_e32 v126, v126, v209
	v_mul_f32_e32 v126, v14, v126
	v_fma_f32 v126, v158, v126, v174
	v_mul_f32_e32 v127, v127, v209
	v_mul_f32_e32 v127, v15, v127
	v_fma_f32 v127, v159, v127, v175
	v_cvt_pk_bf16_f32 v180, v124, v125
	v_cvt_pk_bf16_f32 v181, v126, v127
	global_store_dwordx2 v196, v[180:181], s[10:11] offset:1536
	s_nop 0
	v_mul_f32_e32 v128, v128, v210
	v_mul_f32_e32 v128, v0, v128
	v_fma_f32 v128, v144, v128, v160
	v_mul_f32_e32 v129, v129, v210
	v_mul_f32_e32 v129, v1, v129
	v_fma_f32 v129, v145, v129, v161
	v_mul_f32_e32 v130, v130, v210
	v_mul_f32_e32 v130, v2, v130
	v_fma_f32 v130, v146, v130, v162
	v_mul_f32_e32 v131, v131, v210
	v_mul_f32_e32 v131, v3, v131
	v_fma_f32 v131, v147, v131, v163
	v_cvt_pk_bf16_f32 v180, v128, v129
	v_cvt_pk_bf16_f32 v181, v130, v131
	global_store_dwordx2 v196, v[180:181], s[10:11] offset:2048
	s_nop 0
	v_mul_f32_e32 v132, v132, v210
	v_mul_f32_e32 v132, v4, v132
	v_fma_f32 v132, v148, v132, v164
	v_mul_f32_e32 v133, v133, v210
	v_mul_f32_e32 v133, v5, v133
	v_fma_f32 v133, v149, v133, v165
	v_mul_f32_e32 v134, v134, v210
	v_mul_f32_e32 v134, v6, v134
	v_fma_f32 v134, v150, v134, v166
	v_mul_f32_e32 v135, v135, v210
	v_mul_f32_e32 v135, v7, v135
	v_fma_f32 v135, v151, v135, v167
	v_cvt_pk_bf16_f32 v180, v132, v133
	v_cvt_pk_bf16_f32 v181, v134, v135
	global_store_dwordx2 v196, v[180:181], s[10:11] offset:2560
	s_nop 0
	v_mul_f32_e32 v136, v136, v210
	v_mul_f32_e32 v136, v8, v136
	v_fma_f32 v136, v152, v136, v168
	v_mul_f32_e32 v137, v137, v210
	v_mul_f32_e32 v137, v9, v137
	v_fma_f32 v137, v153, v137, v169
	v_mul_f32_e32 v138, v138, v210
	v_mul_f32_e32 v138, v10, v138
	v_fma_f32 v138, v154, v138, v170
	v_mul_f32_e32 v139, v139, v210
	v_mul_f32_e32 v139, v11, v139
	v_fma_f32 v139, v155, v139, v171
	v_cvt_pk_bf16_f32 v180, v136, v137
	v_cvt_pk_bf16_f32 v181, v138, v139
	global_store_dwordx2 v196, v[180:181], s[10:11] offset:3072
	s_nop 0
	v_mul_f32_e32 v140, v140, v210
	v_mul_f32_e32 v140, v12, v140
	v_fma_f32 v140, v156, v140, v172
	v_mul_f32_e32 v141, v141, v210
	v_mul_f32_e32 v141, v13, v141
	v_fma_f32 v141, v157, v141, v173
	v_mul_f32_e32 v142, v142, v210
	v_mul_f32_e32 v142, v14, v142
	v_fma_f32 v142, v158, v142, v174
	v_mul_f32_e32 v143, v143, v210
	v_mul_f32_e32 v143, v15, v143
	v_fma_f32 v143, v159, v143, v175
	v_cvt_pk_bf16_f32 v180, v140, v141
	v_cvt_pk_bf16_f32 v181, v142, v143
	global_store_dwordx2 v196, v[180:181], s[10:11] offset:3584
	s_nop 0

.LBB0_179:
	s_cmp_eq_u32 s101, 1
	s_cbranch_scc0 .Lst_gs2
	s_mov_b32 s101, 4
	s_sub_u32 s0, s78, 0x160
	s_subb_u32 s1, s79, 0
	s_branch .Lp0_enter
